# weight conversion loops use two LDS tile buffers (one barrier per tile); plus 2.2us start offset of half the workgroups in GEMM kinds 0,2,3
# speedup vs baseline: 1.0052x; 1.0015x over previous
; __device__ __forceinline__ bf16_t f2bf(float f) { unsigned u = __float_as_uint(f); u += 0x7FFFu + ((u >> 16) & 1u); return (bf16_t)(u >> 16); }
;     ...
;     for (int t_ = first; t_ < ntile * ((REP & 1) + 1); t_ += gridDim.x) { const int t = t_ % ntile;
;         const int r0 = (t / nkt) * 64, k0 = (t % nkt) * 64;
;         __syncthreads();
; #pragma unroll
;         for (int i = 0; i < 8; ++i) { const int kk = i * 8 + w; tile[kk * 65 + lane] = src(k0 + kk, r0 + lane); }
;         __syncthreads();
; #pragma unroll
;         for (int i = 0; i < 8; ++i) { const int j = i * 8 + w; Bt[(size_t)(r0 + j) * ld + k0 + lane] = f2bf(tile[lane * 65 + j]); }
; __device__ void convert_phase(unsigned char* smem, const Params& p, int l) {
;     ...
;       conv_tiles(tile, wt + W_UP1, 5632, 1024, 0, [=](int k, int r) { const int col = (r >> 5) * 16 + (r & 15); return gn[k] * (((r >> 4) & 1) ? wu[(size_t)k * DFF + col] : wg[(size_t)k * DFF + col]); }); }
.Lcv307_pj:
	v_add_u32_e32 v95, 0x4400, v7
	s_barrier
.Lcv307_top:
	s_waitcnt vmcnt(31)
	v_mul_f32_e32 v32, v34, v42
	s_waitcnt vmcnt(30)
	v_mul_f32_e32 v33, v35, v43
	s_waitcnt vmcnt(29)
	v_mul_f32_e32 v34, v36, v44
	s_waitcnt vmcnt(28)
	v_mul_f32_e32 v35, v37, v45
	s_waitcnt vmcnt(27)
	v_mul_f32_e32 v36, v38, v46
	s_waitcnt vmcnt(26)
	v_mul_f32_e32 v37, v39, v47
	s_waitcnt vmcnt(25)
	v_mul_f32_e32 v38, v40, v48
	s_waitcnt vmcnt(24)
	v_mul_f32_e32 v39, v41, v49
	ds_write_b32 v15, v32
	ds_write_b32 v15, v33 offset:2080
	ds_write_b32 v15, v34 offset:4160
	ds_write_b32 v15, v35 offset:6240
	ds_write_b32 v15, v36 offset:8320
	ds_write_b32 v15, v37 offset:10400
	ds_write_b32 v15, v38 offset:12480
	ds_write_b32 v15, v39 offset:14560
	s_waitcnt lgkmcnt(0)
	s_barrier
	ds_read2_b32 v[32:33], v7 offset1:8
	ds_read2_b32 v[34:35], v7 offset0:16 offset1:24
	ds_read2_b32 v[36:37], v7 offset0:32 offset1:40
	ds_read2_b32 v[38:39], v7 offset0:48 offset1:56
	s_waitcnt lgkmcnt(3)
	v_bfe_u32 v40, v32, 16, 1
	v_bfe_u32 v41, v33, 16, 1
	s_waitcnt lgkmcnt(2)
	v_bfe_u32 v42, v34, 16, 1
	v_bfe_u32 v43, v35, 16, 1
	s_waitcnt lgkmcnt(1)
	v_bfe_u32 v44, v36, 16, 1
	v_bfe_u32 v45, v37, 16, 1
	s_waitcnt lgkmcnt(0)
	v_bfe_u32 v46, v38, 16, 1
	v_bfe_u32 v47, v39, 16, 1
	v_add3_u32 v32, v32, v40, s88
	v_add3_u32 v33, v33, v41, s88
	v_add3_u32 v34, v34, v42, s88
	v_add3_u32 v35, v35, v43, s88
	v_add3_u32 v36, v36, v44, s88
	v_add3_u32 v37, v37, v45, s88
	v_add3_u32 v38, v38, v46, s88
	v_add3_u32 v39, v39, v47, s88
	global_store_short_d16_hi v[16:17], v32, off
	global_store_short_d16_hi v[18:19], v33, off
	global_store_short_d16_hi v[20:21], v34, off
	global_store_short_d16_hi v[22:23], v35, off
	global_store_short_d16_hi v[24:25], v36, off
	global_store_short_d16_hi v[26:27], v37, off
	global_store_short_d16_hi v[28:29], v38, off
	global_store_short_d16_hi v[30:31], v39, off
	s_lshl_b32 s98, s5, 1
	s_add_i32 s98, s98, s11
	s_cmp_lt_i32 s98, 0x580
	s_cbranch_scc0 .Lcv307_s0
	s_mul_hi_i32 s8, s98, 0x2e8ba2e9
	s_lshr_b32 s9, s8, 31
	s_ashr_i32 s8, s8, 8
	s_add_i32 s8, s8, s9
	s_mulk_i32 s8, 0x580
	s_sub_i32 s8, s98, s8
	s_sext_i32_i16 s9, s8
	s_bfe_u32 s9, s9, 0x4001b
	s_add_i32 s9, s8, s9
	s_sext_i32_i16 s16, s9
	s_and_b32 s9, s9, 0xfff0
	s_lshl_b32 s16, s16, 2
	s_sub_i32 s8, s8, s9
	s_and_b32 s9, s16, 0xffffffc0
	v_or_b32_e32 v16, s9, v4
	s_sext_i32_i16 s8, s8
	v_ashrrev_i32_e32 v17, 1, v16
	s_lshl_b32 s8, s8, 6
	v_and_or_b32 v18, v17, -16, v6
	v_add_u32_e32 v16, s8, v5
	v_ashrrev_i32_e32 v19, 31, v18
	v_ashrrev_i32_e32 v17, 31, v16
	v_lshl_add_u64 v[18:19], v[18:19], 2, v[0:1]
	v_add_u32_e32 v22, s8, v8
	v_add_u32_e32 v23, s8, v9
	v_add_u32_e32 v24, s8, v10
	v_add_u32_e32 v26, s8, v11
	v_add_u32_e32 v28, s8, v12
	v_add_u32_e32 v30, s8, v13
	v_add_u32_e32 v32, s8, v14
	v_lshl_add_u64 v[20:21], v[16:17], 2, s[6:7]
	v_mad_i64_i32 v[16:17], s[16:17], v16, s33, v[18:19]
	global_load_dword v34, v[20:21], off
	global_load_dword v35, v[20:21], off offset:32
	global_load_dword v36, v[20:21], off offset:64
	global_load_dword v37, v[20:21], off offset:96
	global_load_dword v38, v[20:21], off offset:128
	global_load_dword v39, v[20:21], off offset:160
	global_load_dword v40, v[20:21], off offset:192
	global_load_dword v41, v[20:21], off offset:224
	v_mad_i64_i32 v[20:21], s[16:17], v22, s33, v[18:19]
	v_mad_i64_i32 v[22:23], s[16:17], v23, s33, v[18:19]
	v_mad_i64_i32 v[24:25], s[16:17], v24, s33, v[18:19]
	v_mad_i64_i32 v[26:27], s[16:17], v26, s33, v[18:19]
	v_mad_i64_i32 v[28:29], s[16:17], v28, s33, v[18:19]
	v_mad_i64_i32 v[30:31], s[16:17], v30, s33, v[18:19]
	v_mad_i64_i32 v[18:19], s[16:17], v32, s33, v[18:19]
	global_load_dword v42, v[16:17], off
	global_load_dword v43, v[20:21], off
	global_load_dword v44, v[22:23], off
	global_load_dword v45, v[24:25], off
	global_load_dword v46, v[26:27], off
	global_load_dword v47, v[28:29], off
	global_load_dword v48, v[30:31], off
	global_load_dword v49, v[18:19], off
	v_add_u32_e32 v16, s9, v5
	v_add_u32_e32 v18, s9, v8
	v_add_u32_e32 v20, s9, v9
	v_add_u32_e32 v22, s9, v10
	v_add_u32_e32 v24, s9, v11
	v_add_u32_e32 v26, s9, v12
	v_add_u32_e32 v28, s9, v13
	v_add_u32_e32 v30, s9, v14
	s_ashr_i32 s9, s8, 31
	v_ashrrev_i32_e32 v17, 31, v16
	v_ashrrev_i32_e32 v19, 31, v18
	v_ashrrev_i32_e32 v21, 31, v20
	v_ashrrev_i32_e32 v23, 31, v22
	v_ashrrev_i32_e32 v25, 31, v24
	v_ashrrev_i32_e32 v27, 31, v26
	v_ashrrev_i32_e32 v29, 31, v28
	v_ashrrev_i32_e32 v31, 31, v30
	v_lshl_add_u64 v[32:33], s[8:9], 1, v[2:3]
	v_lshlrev_b64 v[16:17], 11, v[16:17]
	v_lshlrev_b64 v[18:19], 11, v[18:19]
	v_lshlrev_b64 v[20:21], 11, v[20:21]
	v_lshlrev_b64 v[22:23], 11, v[22:23]
	v_lshlrev_b64 v[24:25], 11, v[24:25]
	v_lshlrev_b64 v[26:27], 11, v[26:27]
	v_lshlrev_b64 v[28:29], 11, v[28:29]
	v_lshlrev_b64 v[30:31], 11, v[30:31]
	v_lshl_add_u64 v[16:17], v[32:33], 0, v[16:17]
	v_lshl_add_u64 v[18:19], v[32:33], 0, v[18:19]
	v_lshl_add_u64 v[20:21], v[32:33], 0, v[20:21]
	v_lshl_add_u64 v[22:23], v[32:33], 0, v[22:23]
	v_lshl_add_u64 v[24:25], v[32:33], 0, v[24:25]
	v_lshl_add_u64 v[26:27], v[32:33], 0, v[26:27]
	v_lshl_add_u64 v[28:29], v[32:33], 0, v[28:29]
	v_lshl_add_u64 v[30:31], v[32:33], 0, v[30:31]
	s_branch .Lcv307_n0

; __device__ __forceinline__ bf16_t f2bf(float f) { unsigned u = __float_as_uint(f); u += 0x7FFFu + ((u >> 16) & 1u); return (bf16_t)(u >> 16); }
;     ...
;     for (int t_ = first; t_ < ntile * ((REP & 1) + 1); t_ += gridDim.x) { const int t = t_ % ntile;
;         const int r0 = (t / nkt) * 64, k0 = (t % nkt) * 64;
;         __syncthreads();
; #pragma unroll
;         for (int i = 0; i < 8; ++i) { const int kk = i * 8 + w; tile[kk * 65 + lane] = src(k0 + kk, r0 + lane); }
;         __syncthreads();
; #pragma unroll
;         for (int i = 0; i < 8; ++i) { const int j = i * 8 + w; Bt[(size_t)(r0 + j) * ld + k0 + lane] = f2bf(tile[lane * 65 + j]); }
; __device__ void convert_phase(unsigned char* smem, const Params& p, int l) {
;     ...
;       conv_tiles(tile, wt + W_UP1, 5632, 1024, 0, [=](int k, int r) { const int col = (r >> 5) * 16 + (r & 15); return gn[k] * (((r >> 4) & 1) ? wu[(size_t)k * DFF + col] : wg[(size_t)k * DFF + col]); }); }
.Lcv307_n0:
	s_add_i32 s11, s11, s5
	s_cmp_lt_i32 s11, 0x580
	s_cbranch_scc0 .LBB0_308
	s_waitcnt vmcnt(31)
	v_mul_f32_e32 v72, v74, v82
	s_waitcnt vmcnt(30)
	v_mul_f32_e32 v73, v75, v83
	s_waitcnt vmcnt(29)
	v_mul_f32_e32 v74, v76, v84
	s_waitcnt vmcnt(28)
	v_mul_f32_e32 v75, v77, v85
	s_waitcnt vmcnt(27)
	v_mul_f32_e32 v76, v78, v86
	s_waitcnt vmcnt(26)
	v_mul_f32_e32 v77, v79, v87
	s_waitcnt vmcnt(25)
	v_mul_f32_e32 v78, v80, v88
	s_waitcnt vmcnt(24)
	v_mul_f32_e32 v79, v81, v89
	ds_write_b32 v15, v72 offset:17408
	ds_write_b32 v15, v73 offset:19488
	ds_write_b32 v15, v74 offset:21568
	ds_write_b32 v15, v75 offset:23648
	ds_write_b32 v15, v76 offset:25728
	ds_write_b32 v15, v77 offset:27808
	ds_write_b32 v15, v78 offset:29888
	ds_write_b32 v15, v79 offset:31968
	s_waitcnt lgkmcnt(0)
	s_barrier
	ds_read2_b32 v[72:73], v95 offset1:8
	ds_read2_b32 v[74:75], v95 offset0:16 offset1:24
	ds_read2_b32 v[76:77], v95 offset0:32 offset1:40
	ds_read2_b32 v[78:79], v95 offset0:48 offset1:56
	s_waitcnt lgkmcnt(3)
	v_bfe_u32 v80, v72, 16, 1
	v_bfe_u32 v81, v73, 16, 1
	s_waitcnt lgkmcnt(2)
	v_bfe_u32 v82, v74, 16, 1
	v_bfe_u32 v83, v75, 16, 1
	s_waitcnt lgkmcnt(1)
	v_bfe_u32 v84, v76, 16, 1
	v_bfe_u32 v85, v77, 16, 1
	s_waitcnt lgkmcnt(0)
	v_bfe_u32 v86, v78, 16, 1
	v_bfe_u32 v87, v79, 16, 1
	v_add3_u32 v72, v72, v80, s88
	v_add3_u32 v73, v73, v81, s88
	v_add3_u32 v74, v74, v82, s88
	v_add3_u32 v75, v75, v83, s88
	v_add3_u32 v76, v76, v84, s88
	v_add3_u32 v77, v77, v85, s88
	v_add3_u32 v78, v78, v86, s88
	v_add3_u32 v79, v79, v87, s88
	global_store_short_d16_hi v[56:57], v72, off
	global_store_short_d16_hi v[58:59], v73, off
	global_store_short_d16_hi v[60:61], v74, off
	global_store_short_d16_hi v[62:63], v75, off
	global_store_short_d16_hi v[64:65], v76, off
	global_store_short_d16_hi v[66:67], v77, off
	global_store_short_d16_hi v[68:69], v78, off
	global_store_short_d16_hi v[70:71], v79, off
	s_lshl_b32 s98, s5, 1
	s_add_i32 s98, s98, s11
	s_cmp_lt_i32 s98, 0x580
	s_cbranch_scc0 .Lcv307_s1
	s_mul_hi_i32 s8, s98, 0x2e8ba2e9
	s_lshr_b32 s9, s8, 31
	s_ashr_i32 s8, s8, 8
	s_add_i32 s8, s8, s9
	s_mulk_i32 s8, 0x580
	s_sub_i32 s8, s98, s8
	s_sext_i32_i16 s9, s8
	s_bfe_u32 s9, s9, 0x4001b
	s_add_i32 s9, s8, s9
	s_sext_i32_i16 s16, s9
	s_and_b32 s9, s9, 0xfff0
	s_lshl_b32 s16, s16, 2
	s_sub_i32 s8, s8, s9
	s_and_b32 s9, s16, 0xffffffc0
	v_or_b32_e32 v56, s9, v4
	s_sext_i32_i16 s8, s8
	v_ashrrev_i32_e32 v57, 1, v56
	s_lshl_b32 s8, s8, 6
	v_and_or_b32 v58, v57, -16, v6
	v_add_u32_e32 v56, s8, v5
	v_ashrrev_i32_e32 v59, 31, v58
	v_ashrrev_i32_e32 v57, 31, v56
	v_lshl_add_u64 v[58:59], v[58:59], 2, v[0:1]
	v_add_u32_e32 v62, s8, v8
	v_add_u32_e32 v63, s8, v9
	v_add_u32_e32 v64, s8, v10
	v_add_u32_e32 v66, s8, v11
	v_add_u32_e32 v68, s8, v12
	v_add_u32_e32 v70, s8, v13
	v_add_u32_e32 v72, s8, v14
	v_lshl_add_u64 v[60:61], v[56:57], 2, s[6:7]
	v_mad_i64_i32 v[56:57], s[16:17], v56, s33, v[58:59]
	global_load_dword v74, v[60:61], off
	global_load_dword v75, v[60:61], off offset:32
	global_load_dword v76, v[60:61], off offset:64
	global_load_dword v77, v[60:61], off offset:96
	global_load_dword v78, v[60:61], off offset:128
	global_load_dword v79, v[60:61], off offset:160
	global_load_dword v80, v[60:61], off offset:192
	global_load_dword v81, v[60:61], off offset:224
	v_mad_i64_i32 v[60:61], s[16:17], v62, s33, v[58:59]
	v_mad_i64_i32 v[62:63], s[16:17], v63, s33, v[58:59]
	v_mad_i64_i32 v[64:65], s[16:17], v64, s33, v[58:59]
	v_mad_i64_i32 v[66:67], s[16:17], v66, s33, v[58:59]
	v_mad_i64_i32 v[68:69], s[16:17], v68, s33, v[58:59]
	v_mad_i64_i32 v[70:71], s[16:17], v70, s33, v[58:59]
	v_mad_i64_i32 v[58:59], s[16:17], v72, s33, v[58:59]
	global_load_dword v82, v[56:57], off
	global_load_dword v83, v[60:61], off
	global_load_dword v84, v[62:63], off
	global_load_dword v85, v[64:65], off
	global_load_dword v86, v[66:67], off
	global_load_dword v87, v[68:69], off
	global_load_dword v88, v[70:71], off
	global_load_dword v89, v[58:59], off
	v_add_u32_e32 v56, s9, v5
	v_add_u32_e32 v58, s9, v8
	v_add_u32_e32 v60, s9, v9
	v_add_u32_e32 v62, s9, v10
	v_add_u32_e32 v64, s9, v11
	v_add_u32_e32 v66, s9, v12
	v_add_u32_e32 v68, s9, v13
	v_add_u32_e32 v70, s9, v14
	s_ashr_i32 s9, s8, 31
	v_ashrrev_i32_e32 v57, 31, v56
	v_ashrrev_i32_e32 v59, 31, v58
	v_ashrrev_i32_e32 v61, 31, v60
	v_ashrrev_i32_e32 v63, 31, v62
	v_ashrrev_i32_e32 v65, 31, v64
	v_ashrrev_i32_e32 v67, 31, v66
	v_ashrrev_i32_e32 v69, 31, v68
	v_ashrrev_i32_e32 v71, 31, v70
	v_lshl_add_u64 v[72:73], s[8:9], 1, v[2:3]
	v_lshlrev_b64 v[56:57], 11, v[56:57]
	v_lshlrev_b64 v[58:59], 11, v[58:59]
	v_lshlrev_b64 v[60:61], 11, v[60:61]
	v_lshlrev_b64 v[62:63], 11, v[62:63]
	v_lshlrev_b64 v[64:65], 11, v[64:65]
	v_lshlrev_b64 v[66:67], 11, v[66:67]
	v_lshlrev_b64 v[68:69], 11, v[68:69]
	v_lshlrev_b64 v[70:71], 11, v[70:71]
	v_lshl_add_u64 v[56:57], v[72:73], 0, v[56:57]
	v_lshl_add_u64 v[58:59], v[72:73], 0, v[58:59]
	v_lshl_add_u64 v[60:61], v[72:73], 0, v[60:61]
	v_lshl_add_u64 v[62:63], v[72:73], 0, v[62:63]
	v_lshl_add_u64 v[64:65], v[72:73], 0, v[64:65]
	v_lshl_add_u64 v[66:67], v[72:73], 0, v[66:67]
	v_lshl_add_u64 v[68:69], v[72:73], 0, v[68:69]
	v_lshl_add_u64 v[70:71], v[72:73], 0, v[70:71]
	s_branch .Lcv307_n1

; __device__ __forceinline__ bf16_t f2bf(float f) { unsigned u = __float_as_uint(f); u += 0x7FFFu + ((u >> 16) & 1u); return (bf16_t)(u >> 16); }
;     ...
;     for (int t_ = first; t_ < ntile * ((REP & 1) + 1); t_ += gridDim.x) { const int t = t_ % ntile;
;         const int r0 = (t / nkt) * 64, k0 = (t % nkt) * 64;
;         __syncthreads();
; #pragma unroll
;         for (int i = 0; i < 8; ++i) { const int kk = i * 8 + w; tile[kk * 65 + lane] = src(k0 + kk, r0 + lane); }
;         __syncthreads();
; #pragma unroll
;         for (int i = 0; i < 8; ++i) { const int j = i * 8 + w; Bt[(size_t)(r0 + j) * ld + k0 + lane] = f2bf(tile[lane * 65 + j]); }
; __device__ void convert_phase(unsigned char* smem, const Params& p, int l) {
;     ...
;     { const float* wd = ((const float*)ldp(4)) + uo; conv_tiles(tile, wt + W_DN1, 1024, 2816, 37, [=](int k, int r) { return wd[(size_t)k * DM + r]; }); }
.Lcv310_pj:
	v_add_u32_e32 v95, 0x4400, v4
	s_barrier
.Lcv310_top:
	s_waitcnt vmcnt(23)
	ds_write_b32 v12, v13
	s_waitcnt vmcnt(22)
	ds_write_b32 v12, v30 offset:2080
	s_waitcnt vmcnt(21)
	ds_write_b32 v12, v31 offset:4160
	s_waitcnt vmcnt(20)
	ds_write_b32 v12, v32 offset:6240
	s_waitcnt vmcnt(19)
	ds_write_b32 v12, v33 offset:8320
	s_waitcnt vmcnt(18)
	ds_write_b32 v12, v34 offset:10400
	s_waitcnt vmcnt(17)
	ds_write_b32 v12, v35 offset:12480
	s_waitcnt vmcnt(16)
	ds_write_b32 v12, v36 offset:14560
	s_waitcnt lgkmcnt(0)
	s_barrier
	ds_read2_b32 v[30:31], v4 offset1:8
	ds_read2_b32 v[32:33], v4 offset0:16 offset1:24
	ds_read2_b32 v[34:35], v4 offset0:32 offset1:40
	ds_read2_b32 v[36:37], v4 offset0:48 offset1:56
	s_waitcnt lgkmcnt(3)
	v_bfe_u32 v13, v30, 16, 1
	v_bfe_u32 v38, v31, 16, 1
	s_waitcnt lgkmcnt(2)
	v_bfe_u32 v39, v32, 16, 1
	v_bfe_u32 v40, v33, 16, 1
	s_waitcnt lgkmcnt(1)
	v_bfe_u32 v41, v34, 16, 1
	v_bfe_u32 v42, v35, 16, 1
	s_waitcnt lgkmcnt(0)
	v_bfe_u32 v43, v36, 16, 1
	v_bfe_u32 v44, v37, 16, 1
	v_add3_u32 v13, v30, v13, s88
	v_add3_u32 v30, v31, v38, s88
	v_add3_u32 v31, v32, v39, s88
	v_add3_u32 v32, v33, v40, s88
	v_add3_u32 v33, v34, v41, s88
	v_add3_u32 v34, v35, v42, s88
	v_add3_u32 v35, v36, v43, s88
	v_add3_u32 v36, v37, v44, s88
	global_store_short_d16_hi v[16:17], v13, off
	global_store_short_d16_hi v[18:19], v30, off
	global_store_short_d16_hi v[20:21], v31, off
	global_store_short_d16_hi v[22:23], v32, off
	global_store_short_d16_hi v[24:25], v33, off
	global_store_short_d16_hi v[26:27], v34, off
	global_store_short_d16_hi v[28:29], v35, off
	global_store_short_d16_hi v[14:15], v36, off
	s_lshl_b32 s98, s5, 1
	s_add_i32 s98, s98, s11
	s_cmp_lt_i32 s98, 0x2c0
	s_cbranch_scc0 .Lcv310_s0
	s_mul_hi_i32 s8, s98, 0x2e8ba2e9
	s_lshr_b32 s9, s8, 31
	s_ashr_i32 s8, s8, 7
	s_add_i32 s8, s8, s9
	s_mulk_i32 s8, 0x2c0
	s_sub_i32 s8, s98, s8
	s_sext_i32_i16 s9, s8
	s_mulk_i32 s9, 0xba3
	s_lshr_b32 s16, s9, 31
	s_ashr_i32 s9, s9, 17
	s_add_i32 s9, s9, s16
	s_sext_i32_i16 s16, s9
	s_mul_i32 s9, s9, 44
	s_sub_i32 s8, s8, s9
	s_sext_i32_i16 s8, s8
	s_lshl_b32 s16, s16, 6
	s_lshl_b32 s8, s8, 6
	v_or_b32_e32 v14, s16, v2
	v_add_u32_e32 v16, s8, v3
	v_ashrrev_i32_e32 v15, 31, v14
	v_add_u32_e32 v18, s8, v5
	v_add_u32_e32 v20, s8, v6
	v_add_u32_e32 v22, s8, v7
	v_add_u32_e32 v24, s8, v8
	v_add_u32_e32 v26, s8, v9
	v_add_u32_e32 v28, s8, v10
	v_add_u32_e32 v30, s8, v11
	v_ashrrev_i32_e32 v17, 31, v16
	v_lshl_add_u64 v[14:15], v[14:15], 2, s[6:7]
	v_ashrrev_i32_e32 v19, 31, v18
	v_ashrrev_i32_e32 v21, 31, v20
	v_ashrrev_i32_e32 v23, 31, v22
	v_ashrrev_i32_e32 v25, 31, v24
	v_ashrrev_i32_e32 v27, 31, v26
	v_ashrrev_i32_e32 v29, 31, v28
	v_ashrrev_i32_e32 v31, 31, v30
	v_lshlrev_b64 v[16:17], 12, v[16:17]
	v_lshlrev_b64 v[18:19], 12, v[18:19]
	v_lshlrev_b64 v[20:21], 12, v[20:21]
	v_lshlrev_b64 v[22:23], 12, v[22:23]
	v_lshlrev_b64 v[24:25], 12, v[24:25]
	v_lshlrev_b64 v[26:27], 12, v[26:27]
	v_lshlrev_b64 v[28:29], 12, v[28:29]
	v_lshlrev_b64 v[30:31], 12, v[30:31]
	v_lshl_add_u64 v[16:17], v[14:15], 0, v[16:17]
	v_lshl_add_u64 v[18:19], v[14:15], 0, v[18:19]
	v_lshl_add_u64 v[20:21], v[14:15], 0, v[20:21]
	v_lshl_add_u64 v[22:23], v[14:15], 0, v[22:23]
	v_lshl_add_u64 v[24:25], v[14:15], 0, v[24:25]
	v_lshl_add_u64 v[26:27], v[14:15], 0, v[26:27]
	v_lshl_add_u64 v[28:29], v[14:15], 0, v[28:29]
	v_lshl_add_u64 v[14:15], v[14:15], 0, v[30:31]
	global_load_dword v13, v[16:17], off
	global_load_dword v30, v[18:19], off
	global_load_dword v31, v[20:21], off
	global_load_dword v32, v[22:23], off
	global_load_dword v33, v[24:25], off
	global_load_dword v34, v[26:27], off
	global_load_dword v35, v[28:29], off
	global_load_dword v36, v[14:15], off
	s_ashr_i32 s9, s8, 31
	v_add_u32_e32 v16, s16, v3
	v_add_u32_e32 v18, s16, v5
	v_add_u32_e32 v20, s16, v6
	v_add_u32_e32 v22, s16, v7
	v_add_u32_e32 v24, s16, v8
	v_add_u32_e32 v26, s16, v9
	v_add_u32_e32 v28, s16, v10
	v_add_u32_e32 v37, s16, v11
	v_lshl_add_u64 v[14:15], s[8:9], 1, v[0:1]
	v_mad_i64_i32 v[16:17], s[8:9], v16, s54, v[14:15]
	v_mad_i64_i32 v[18:19], s[8:9], v18, s54, v[14:15]
	v_mad_i64_i32 v[20:21], s[8:9], v20, s54, v[14:15]
	v_mad_i64_i32 v[22:23], s[8:9], v22, s54, v[14:15]
	v_mad_i64_i32 v[24:25], s[8:9], v24, s54, v[14:15]
	v_mad_i64_i32 v[26:27], s[8:9], v26, s54, v[14:15]
	v_mad_i64_i32 v[28:29], s[8:9], v28, s54, v[14:15]
	v_mad_i64_i32 v[14:15], s[8:9], v37, s54, v[14:15]
	s_branch .Lcv310_n0

; __device__ __forceinline__ bf16_t f2bf(float f) { unsigned u = __float_as_uint(f); u += 0x7FFFu + ((u >> 16) & 1u); return (bf16_t)(u >> 16); }
;     ...
;     for (int t_ = first; t_ < ntile * ((REP & 1) + 1); t_ += gridDim.x) { const int t = t_ % ntile;
;         const int r0 = (t / nkt) * 64, k0 = (t % nkt) * 64;
;         __syncthreads();
; #pragma unroll
;         for (int i = 0; i < 8; ++i) { const int kk = i * 8 + w; tile[kk * 65 + lane] = src(k0 + kk, r0 + lane); }
;         __syncthreads();
; #pragma unroll
;         for (int i = 0; i < 8; ++i) { const int j = i * 8 + w; Bt[(size_t)(r0 + j) * ld + k0 + lane] = f2bf(tile[lane * 65 + j]); }
; __device__ void convert_phase(unsigned char* smem, const Params& p, int l) {
;     ...
;     { const float* wd = ((const float*)ldp(4)) + uo; conv_tiles(tile, wt + W_DN1, 1024, 2816, 37, [=](int k, int r) { return wd[(size_t)k * DM + r]; }); }
.Lcv310_n0:
	s_add_i32 s11, s11, s5
	s_cmp_lt_i32 s11, 0x2c0
	s_cbranch_scc0 .LBB0_311
	s_waitcnt vmcnt(23)
	ds_write_b32 v12, v53 offset:17408
	s_waitcnt vmcnt(22)
	ds_write_b32 v12, v70 offset:19488
	s_waitcnt vmcnt(21)
	ds_write_b32 v12, v71 offset:21568
	s_waitcnt vmcnt(20)
	ds_write_b32 v12, v72 offset:23648
	s_waitcnt vmcnt(19)
	ds_write_b32 v12, v73 offset:25728
	s_waitcnt vmcnt(18)
	ds_write_b32 v12, v74 offset:27808
	s_waitcnt vmcnt(17)
	ds_write_b32 v12, v75 offset:29888
	s_waitcnt vmcnt(16)
	ds_write_b32 v12, v76 offset:31968
	s_waitcnt lgkmcnt(0)
	s_barrier
	ds_read2_b32 v[70:71], v95 offset1:8
	ds_read2_b32 v[72:73], v95 offset0:16 offset1:24
	ds_read2_b32 v[74:75], v95 offset0:32 offset1:40
	ds_read2_b32 v[76:77], v95 offset0:48 offset1:56
	s_waitcnt lgkmcnt(3)
	v_bfe_u32 v53, v70, 16, 1
	v_bfe_u32 v78, v71, 16, 1
	s_waitcnt lgkmcnt(2)
	v_bfe_u32 v79, v72, 16, 1
	v_bfe_u32 v80, v73, 16, 1
	s_waitcnt lgkmcnt(1)
	v_bfe_u32 v81, v74, 16, 1
	v_bfe_u32 v82, v75, 16, 1
	s_waitcnt lgkmcnt(0)
	v_bfe_u32 v83, v76, 16, 1
	v_bfe_u32 v84, v77, 16, 1
	v_add3_u32 v53, v70, v53, s88
	v_add3_u32 v70, v71, v78, s88
	v_add3_u32 v71, v72, v79, s88
	v_add3_u32 v72, v73, v80, s88
	v_add3_u32 v73, v74, v81, s88
	v_add3_u32 v74, v75, v82, s88
	v_add3_u32 v75, v76, v83, s88
	v_add3_u32 v76, v77, v84, s88
	global_store_short_d16_hi v[56:57], v53, off
	global_store_short_d16_hi v[58:59], v70, off
	global_store_short_d16_hi v[60:61], v71, off
	global_store_short_d16_hi v[62:63], v72, off
	global_store_short_d16_hi v[64:65], v73, off
	global_store_short_d16_hi v[66:67], v74, off
	global_store_short_d16_hi v[68:69], v75, off
	global_store_short_d16_hi v[54:55], v76, off
	s_lshl_b32 s98, s5, 1
	s_add_i32 s98, s98, s11
	s_cmp_lt_i32 s98, 0x2c0
	s_cbranch_scc0 .Lcv310_s1
	s_mul_hi_i32 s8, s98, 0x2e8ba2e9
	s_lshr_b32 s9, s8, 31
	s_ashr_i32 s8, s8, 7
	s_add_i32 s8, s8, s9
	s_mulk_i32 s8, 0x2c0
	s_sub_i32 s8, s98, s8
	s_sext_i32_i16 s9, s8
	s_mulk_i32 s9, 0xba3
	s_lshr_b32 s16, s9, 31
	s_ashr_i32 s9, s9, 17
	s_add_i32 s9, s9, s16
	s_sext_i32_i16 s16, s9
	s_mul_i32 s9, s9, 44
	s_sub_i32 s8, s8, s9
	s_sext_i32_i16 s8, s8
	s_lshl_b32 s16, s16, 6
	s_lshl_b32 s8, s8, 6
	v_or_b32_e32 v54, s16, v2
	v_add_u32_e32 v56, s8, v3
	v_ashrrev_i32_e32 v55, 31, v54
	v_add_u32_e32 v58, s8, v5
	v_add_u32_e32 v60, s8, v6
	v_add_u32_e32 v62, s8, v7
	v_add_u32_e32 v64, s8, v8
	v_add_u32_e32 v66, s8, v9
	v_add_u32_e32 v68, s8, v10
	v_add_u32_e32 v70, s8, v11
	v_ashrrev_i32_e32 v57, 31, v56
	v_lshl_add_u64 v[54:55], v[54:55], 2, s[6:7]
	v_ashrrev_i32_e32 v59, 31, v58
	v_ashrrev_i32_e32 v61, 31, v60
	v_ashrrev_i32_e32 v63, 31, v62
	v_ashrrev_i32_e32 v65, 31, v64
	v_ashrrev_i32_e32 v67, 31, v66
	v_ashrrev_i32_e32 v69, 31, v68
	v_ashrrev_i32_e32 v71, 31, v70
	v_lshlrev_b64 v[56:57], 12, v[56:57]
	v_lshlrev_b64 v[58:59], 12, v[58:59]
	v_lshlrev_b64 v[60:61], 12, v[60:61]
	v_lshlrev_b64 v[62:63], 12, v[62:63]
	v_lshlrev_b64 v[64:65], 12, v[64:65]
	v_lshlrev_b64 v[66:67], 12, v[66:67]
	v_lshlrev_b64 v[68:69], 12, v[68:69]
	v_lshlrev_b64 v[70:71], 12, v[70:71]
	v_lshl_add_u64 v[56:57], v[54:55], 0, v[56:57]
	v_lshl_add_u64 v[58:59], v[54:55], 0, v[58:59]
	v_lshl_add_u64 v[60:61], v[54:55], 0, v[60:61]
	v_lshl_add_u64 v[62:63], v[54:55], 0, v[62:63]
	v_lshl_add_u64 v[64:65], v[54:55], 0, v[64:65]
	v_lshl_add_u64 v[66:67], v[54:55], 0, v[66:67]
	v_lshl_add_u64 v[68:69], v[54:55], 0, v[68:69]
	v_lshl_add_u64 v[54:55], v[54:55], 0, v[70:71]
	global_load_dword v53, v[56:57], off
	global_load_dword v70, v[58:59], off
	global_load_dword v71, v[60:61], off
	global_load_dword v72, v[62:63], off
	global_load_dword v73, v[64:65], off
	global_load_dword v74, v[66:67], off
	global_load_dword v75, v[68:69], off
	global_load_dword v76, v[54:55], off
	s_ashr_i32 s9, s8, 31
	v_add_u32_e32 v56, s16, v3
	v_add_u32_e32 v58, s16, v5
	v_add_u32_e32 v60, s16, v6
	v_add_u32_e32 v62, s16, v7
	v_add_u32_e32 v64, s16, v8
	v_add_u32_e32 v66, s16, v9
	v_add_u32_e32 v68, s16, v10
	v_add_u32_e32 v77, s16, v11
	v_lshl_add_u64 v[54:55], s[8:9], 1, v[0:1]
	v_mad_i64_i32 v[56:57], s[8:9], v56, s54, v[54:55]
	v_mad_i64_i32 v[58:59], s[8:9], v58, s54, v[54:55]
	v_mad_i64_i32 v[60:61], s[8:9], v60, s54, v[54:55]
	v_mad_i64_i32 v[62:63], s[8:9], v62, s54, v[54:55]
	v_mad_i64_i32 v[64:65], s[8:9], v64, s54, v[54:55]
	v_mad_i64_i32 v[66:67], s[8:9], v66, s54, v[54:55]
	v_mad_i64_i32 v[68:69], s[8:9], v68, s54, v[54:55]
	v_mad_i64_i32 v[54:55], s[8:9], v77, s54, v[54:55]
	s_branch .Lcv310_n1

; __device__ __forceinline__ bf16_t f2bf(float f) { unsigned u = __float_as_uint(f); u += 0x7FFFu + ((u >> 16) & 1u); return (bf16_t)(u >> 16); }
;     ...
;     for (int t_ = first; t_ < ntile * ((REP & 1) + 1); t_ += gridDim.x) { const int t = t_ % ntile;
;         const int r0 = (t / nkt) * 64, k0 = (t % nkt) * 64;
;         __syncthreads();
; #pragma unroll
;         for (int i = 0; i < 8; ++i) { const int kk = i * 8 + w; tile[kk * 65 + lane] = src(k0 + kk, r0 + lane); }
;         __syncthreads();
; #pragma unroll
;         for (int i = 0; i < 8; ++i) { const int j = i * 8 + w; Bt[(size_t)(r0 + j) * ld + k0 + lane] = f2bf(tile[lane * 65 + j]); }
; __device__ void convert_phase(unsigned char* smem, const Params& p, int l) {
;     ...
;       conv_tiles(tile, wt + W_HYRG, 2560, 1024, 71, [=](int k, int r) { const int col = r < HYC ? r : r + QKVC; return gn[k] * wi[(size_t)k * INC + col]; });
.Lcv313_top:
	s_waitcnt vmcnt(31)
	v_mul_f32_e32 v13, v13, v39
	s_waitcnt vmcnt(30)
	v_mul_f32_e32 v30, v32, v40
	s_waitcnt vmcnt(29)
	v_mul_f32_e32 v31, v33, v41
	s_waitcnt vmcnt(28)
	v_mul_f32_e32 v32, v34, v42
	s_waitcnt vmcnt(27)
	v_mul_f32_e32 v33, v35, v43
	s_waitcnt vmcnt(26)
	v_mul_f32_e32 v34, v36, v44
	s_waitcnt vmcnt(25)
	v_mul_f32_e32 v35, v37, v45
	s_waitcnt vmcnt(24)
	v_mul_f32_e32 v36, v38, v46
	ds_write_b32 v12, v13
	ds_write_b32 v12, v30 offset:2080
	ds_write_b32 v12, v31 offset:4160
	ds_write_b32 v12, v32 offset:6240
	ds_write_b32 v12, v33 offset:8320
	ds_write_b32 v12, v34 offset:10400
	ds_write_b32 v12, v35 offset:12480
	ds_write_b32 v12, v36 offset:14560
	s_waitcnt lgkmcnt(0)
	s_barrier
	ds_read2_b32 v[30:31], v4 offset1:8
	ds_read2_b32 v[32:33], v4 offset0:16 offset1:24
	ds_read2_b32 v[34:35], v4 offset0:32 offset1:40
	ds_read2_b32 v[36:37], v4 offset0:48 offset1:56
	s_waitcnt lgkmcnt(3)
	v_bfe_u32 v13, v30, 16, 1
	v_bfe_u32 v38, v31, 16, 1
	s_waitcnt lgkmcnt(2)
	v_bfe_u32 v39, v32, 16, 1
	v_bfe_u32 v40, v33, 16, 1
	s_waitcnt lgkmcnt(1)
	v_bfe_u32 v41, v34, 16, 1
	v_bfe_u32 v42, v35, 16, 1
	s_waitcnt lgkmcnt(0)
	v_bfe_u32 v43, v36, 16, 1
	v_bfe_u32 v44, v37, 16, 1
	v_add3_u32 v13, v30, v13, s88
	v_add3_u32 v30, v31, v38, s88
	v_add3_u32 v31, v32, v39, s88
	v_add3_u32 v32, v33, v40, s88
	v_add3_u32 v33, v34, v41, s88
	v_add3_u32 v34, v35, v42, s88
	v_add3_u32 v35, v36, v43, s88
	v_add3_u32 v36, v37, v44, s88
	global_store_short_d16_hi v[14:15], v13, off
	global_store_short_d16_hi v[16:17], v30, off
	global_store_short_d16_hi v[18:19], v31, off
	global_store_short_d16_hi v[20:21], v32, off
	global_store_short_d16_hi v[22:23], v33, off
	global_store_short_d16_hi v[24:25], v34, off
	global_store_short_d16_hi v[26:27], v35, off
	global_store_short_d16_hi v[28:29], v36, off
	s_lshl_b32 s98, s5, 1
	s_add_i32 s98, s98, s18
	s_cmp_lt_i32 s98, 0x280
	s_cbranch_scc0 .Lcv313_s0
	s_mul_hi_i32 s10, s98, 0x66666667
	s_lshr_b32 s19, s10, 31
	s_ashr_i32 s10, s10, 8
	s_add_i32 s10, s10, s19
	s_mulk_i32 s10, 0x280
	s_sub_i32 s10, s98, s10
	s_sext_i32_i16 s19, s10
	s_bfe_u32 s19, s19, 0x4001b
	s_add_i32 s19, s10, s19
	s_sext_i32_i16 s20, s19
	s_and_b32 s19, s19, 0xfff0
	s_lshl_b32 s20, s20, 2
	s_sub_i32 s10, s10, s19
	s_and_b32 s19, s20, 0xffffffc0
	s_movk_i32 s11, 0x600
	v_or_b32_e32 v13, s19, v2
	s_sext_i32_i16 s10, s10
	v_add_u32_e32 v15, 0x1200, v13
	v_cmp_gt_i32_e32 vcc, s11, v13
	s_lshl_b32 s10, s10, 6
	v_add_u32_e32 v14, s10, v3
	v_cndmask_b32_e32 v16, v15, v13, vcc
	v_ashrrev_i32_e32 v17, 31, v16
	v_ashrrev_i32_e32 v15, 31, v14
	v_lshl_add_u64 v[16:17], v[16:17], 2, s[6:7]
	v_add_u32_e32 v20, s10, v5
	v_add_u32_e32 v21, s10, v6
	v_add_u32_e32 v22, s10, v7
	v_add_u32_e32 v24, s10, v8
	v_add_u32_e32 v26, s10, v9
	v_add_u32_e32 v28, s10, v10
	v_add_u32_e32 v30, s10, v11
	v_lshl_add_u64 v[18:19], v[14:15], 2, s[8:9]
	v_mad_i64_i32 v[14:15], s[20:21], v14, s94, v[16:17]
	global_load_dword v13, v[18:19], off
	global_load_dword v32, v[18:19], off offset:32
	global_load_dword v33, v[18:19], off offset:64
	global_load_dword v34, v[18:19], off offset:96
	global_load_dword v35, v[18:19], off offset:128
	global_load_dword v36, v[18:19], off offset:160
	global_load_dword v37, v[18:19], off offset:192
	global_load_dword v38, v[18:19], off offset:224
	v_mad_i64_i32 v[18:19], s[20:21], v20, s94, v[16:17]
	v_mad_i64_i32 v[20:21], s[20:21], v21, s94, v[16:17]
	v_mad_i64_i32 v[22:23], s[20:21], v22, s94, v[16:17]
	v_mad_i64_i32 v[24:25], s[20:21], v24, s94, v[16:17]
	v_mad_i64_i32 v[26:27], s[20:21], v26, s94, v[16:17]
	v_mad_i64_i32 v[28:29], s[20:21], v28, s94, v[16:17]
	v_mad_i64_i32 v[16:17], s[20:21], v30, s94, v[16:17]
	global_load_dword v39, v[14:15], off
	global_load_dword v40, v[18:19], off
	global_load_dword v41, v[20:21], off
	global_load_dword v42, v[22:23], off
	global_load_dword v43, v[24:25], off
	global_load_dword v44, v[26:27], off
	global_load_dword v45, v[28:29], off
	global_load_dword v46, v[16:17], off
	v_add_u32_e32 v14, s19, v3
	v_add_u32_e32 v16, s19, v5
	v_add_u32_e32 v18, s19, v6
	v_add_u32_e32 v20, s19, v7
	v_add_u32_e32 v22, s19, v8
	v_add_u32_e32 v24, s19, v9
	v_add_u32_e32 v26, s19, v10
	v_add_u32_e32 v28, s19, v11
	s_ashr_i32 s11, s10, 31
	v_ashrrev_i32_e32 v15, 31, v14
	v_ashrrev_i32_e32 v17, 31, v16
	v_ashrrev_i32_e32 v19, 31, v18
	v_ashrrev_i32_e32 v21, 31, v20
	v_ashrrev_i32_e32 v23, 31, v22
	v_ashrrev_i32_e32 v25, 31, v24
	v_ashrrev_i32_e32 v27, 31, v26
	v_ashrrev_i32_e32 v29, 31, v28
	v_lshl_add_u64 v[30:31], s[10:11], 1, v[0:1]
	v_lshlrev_b64 v[14:15], 11, v[14:15]
	v_lshlrev_b64 v[16:17], 11, v[16:17]
	v_lshlrev_b64 v[18:19], 11, v[18:19]
	v_lshlrev_b64 v[20:21], 11, v[20:21]
	v_lshlrev_b64 v[22:23], 11, v[22:23]
	v_lshlrev_b64 v[24:25], 11, v[24:25]
	v_lshlrev_b64 v[26:27], 11, v[26:27]
	v_lshlrev_b64 v[28:29], 11, v[28:29]
	v_lshl_add_u64 v[14:15], v[30:31], 0, v[14:15]
	v_lshl_add_u64 v[16:17], v[30:31], 0, v[16:17]
	v_lshl_add_u64 v[18:19], v[30:31], 0, v[18:19]
	v_lshl_add_u64 v[20:21], v[30:31], 0, v[20:21]
	v_lshl_add_u64 v[22:23], v[30:31], 0, v[22:23]
	v_lshl_add_u64 v[24:25], v[30:31], 0, v[24:25]
	v_lshl_add_u64 v[26:27], v[30:31], 0, v[26:27]
	v_lshl_add_u64 v[28:29], v[30:31], 0, v[28:29]
	s_branch .Lcv313_n0

; __device__ __forceinline__ bf16_t f2bf(float f) { unsigned u = __float_as_uint(f); u += 0x7FFFu + ((u >> 16) & 1u); return (bf16_t)(u >> 16); }
;     ...
;     for (int t_ = first; t_ < ntile * ((REP & 1) + 1); t_ += gridDim.x) { const int t = t_ % ntile;
;         const int r0 = (t / nkt) * 64, k0 = (t % nkt) * 64;
;         __syncthreads();
; #pragma unroll
;         for (int i = 0; i < 8; ++i) { const int kk = i * 8 + w; tile[kk * 65 + lane] = src(k0 + kk, r0 + lane); }
;         __syncthreads();
; #pragma unroll
;         for (int i = 0; i < 8; ++i) { const int j = i * 8 + w; Bt[(size_t)(r0 + j) * ld + k0 + lane] = f2bf(tile[lane * 65 + j]); }
; __device__ void convert_phase(unsigned char* smem, const Params& p, int l) {
;     ...
;       conv_tiles(tile, wt + W_HYRG, 2560, 1024, 71, [=](int k, int r) { const int col = r < HYC ? r : r + QKVC; return gn[k] * wi[(size_t)k * INC + col]; });
.Lcv313_n0:
	s_add_i32 s18, s18, s5
	s_cmp_lt_i32 s18, 0x280
	s_cbranch_scc0 .LBB0_314
	s_waitcnt vmcnt(31)
	v_mul_f32_e32 v53, v53, v79
	s_waitcnt vmcnt(30)
	v_mul_f32_e32 v70, v72, v80
	s_waitcnt vmcnt(29)
	v_mul_f32_e32 v71, v73, v81
	s_waitcnt vmcnt(28)
	v_mul_f32_e32 v72, v74, v82
	s_waitcnt vmcnt(27)
	v_mul_f32_e32 v73, v75, v83
	s_waitcnt vmcnt(26)
	v_mul_f32_e32 v74, v76, v84
	s_waitcnt vmcnt(25)
	v_mul_f32_e32 v75, v77, v85
	s_waitcnt vmcnt(24)
	v_mul_f32_e32 v76, v78, v86
	ds_write_b32 v12, v53 offset:17408
	ds_write_b32 v12, v70 offset:19488
	ds_write_b32 v12, v71 offset:21568
	ds_write_b32 v12, v72 offset:23648
	ds_write_b32 v12, v73 offset:25728
	ds_write_b32 v12, v74 offset:27808
	ds_write_b32 v12, v75 offset:29888
	ds_write_b32 v12, v76 offset:31968
	s_waitcnt lgkmcnt(0)
	s_barrier
	ds_read2_b32 v[70:71], v95 offset1:8
	ds_read2_b32 v[72:73], v95 offset0:16 offset1:24
	ds_read2_b32 v[74:75], v95 offset0:32 offset1:40
	ds_read2_b32 v[76:77], v95 offset0:48 offset1:56
	s_waitcnt lgkmcnt(3)
	v_bfe_u32 v53, v70, 16, 1
	v_bfe_u32 v78, v71, 16, 1
	s_waitcnt lgkmcnt(2)
	v_bfe_u32 v79, v72, 16, 1
	v_bfe_u32 v80, v73, 16, 1
	s_waitcnt lgkmcnt(1)
	v_bfe_u32 v81, v74, 16, 1
	v_bfe_u32 v82, v75, 16, 1
	s_waitcnt lgkmcnt(0)
	v_bfe_u32 v83, v76, 16, 1
	v_bfe_u32 v84, v77, 16, 1
	v_add3_u32 v53, v70, v53, s88
	v_add3_u32 v70, v71, v78, s88
	v_add3_u32 v71, v72, v79, s88
	v_add3_u32 v72, v73, v80, s88
	v_add3_u32 v73, v74, v81, s88
	v_add3_u32 v74, v75, v82, s88
	v_add3_u32 v75, v76, v83, s88
	v_add3_u32 v76, v77, v84, s88
	global_store_short_d16_hi v[54:55], v53, off
	global_store_short_d16_hi v[56:57], v70, off
	global_store_short_d16_hi v[58:59], v71, off
	global_store_short_d16_hi v[60:61], v72, off
	global_store_short_d16_hi v[62:63], v73, off
	global_store_short_d16_hi v[64:65], v74, off
	global_store_short_d16_hi v[66:67], v75, off
	global_store_short_d16_hi v[68:69], v76, off
	s_lshl_b32 s98, s5, 1
	s_add_i32 s98, s98, s18
	s_cmp_lt_i32 s98, 0x280
	s_cbranch_scc0 .Lcv313_s1
	s_mul_hi_i32 s10, s98, 0x66666667
	s_lshr_b32 s19, s10, 31
	s_ashr_i32 s10, s10, 8
	s_add_i32 s10, s10, s19
	s_mulk_i32 s10, 0x280
	s_sub_i32 s10, s98, s10
	s_sext_i32_i16 s19, s10
	s_bfe_u32 s19, s19, 0x4001b
	s_add_i32 s19, s10, s19
	s_sext_i32_i16 s20, s19
	s_and_b32 s19, s19, 0xfff0
	s_lshl_b32 s20, s20, 2
	s_sub_i32 s10, s10, s19
	s_and_b32 s19, s20, 0xffffffc0
	s_movk_i32 s11, 0x600
	v_or_b32_e32 v53, s19, v2
	s_sext_i32_i16 s10, s10
	v_add_u32_e32 v55, 0x1200, v53
	v_cmp_gt_i32_e32 vcc, s11, v53
	s_lshl_b32 s10, s10, 6
	v_add_u32_e32 v54, s10, v3
	v_cndmask_b32_e32 v56, v55, v53, vcc
	v_ashrrev_i32_e32 v57, 31, v56
	v_ashrrev_i32_e32 v55, 31, v54
	v_lshl_add_u64 v[56:57], v[56:57], 2, s[6:7]
	v_add_u32_e32 v60, s10, v5
	v_add_u32_e32 v61, s10, v6
	v_add_u32_e32 v62, s10, v7
	v_add_u32_e32 v64, s10, v8
	v_add_u32_e32 v66, s10, v9
	v_add_u32_e32 v68, s10, v10
	v_add_u32_e32 v70, s10, v11
	v_lshl_add_u64 v[58:59], v[54:55], 2, s[8:9]
	v_mad_i64_i32 v[54:55], s[20:21], v54, s94, v[56:57]
	global_load_dword v53, v[58:59], off
	global_load_dword v72, v[58:59], off offset:32
	global_load_dword v73, v[58:59], off offset:64
	global_load_dword v74, v[58:59], off offset:96
	global_load_dword v75, v[58:59], off offset:128
	global_load_dword v76, v[58:59], off offset:160
	global_load_dword v77, v[58:59], off offset:192
	global_load_dword v78, v[58:59], off offset:224
	v_mad_i64_i32 v[58:59], s[20:21], v60, s94, v[56:57]
	v_mad_i64_i32 v[60:61], s[20:21], v61, s94, v[56:57]
	v_mad_i64_i32 v[62:63], s[20:21], v62, s94, v[56:57]
	v_mad_i64_i32 v[64:65], s[20:21], v64, s94, v[56:57]
	v_mad_i64_i32 v[66:67], s[20:21], v66, s94, v[56:57]
	v_mad_i64_i32 v[68:69], s[20:21], v68, s94, v[56:57]
	v_mad_i64_i32 v[56:57], s[20:21], v70, s94, v[56:57]
	global_load_dword v79, v[54:55], off
	global_load_dword v80, v[58:59], off
	global_load_dword v81, v[60:61], off
	global_load_dword v82, v[62:63], off
	global_load_dword v83, v[64:65], off
	global_load_dword v84, v[66:67], off
	global_load_dword v85, v[68:69], off
	global_load_dword v86, v[56:57], off
	v_add_u32_e32 v54, s19, v3
	v_add_u32_e32 v56, s19, v5
	v_add_u32_e32 v58, s19, v6
	v_add_u32_e32 v60, s19, v7
	v_add_u32_e32 v62, s19, v8
	v_add_u32_e32 v64, s19, v9
	v_add_u32_e32 v66, s19, v10
	v_add_u32_e32 v68, s19, v11
	s_ashr_i32 s11, s10, 31
	v_ashrrev_i32_e32 v55, 31, v54
	v_ashrrev_i32_e32 v57, 31, v56
	v_ashrrev_i32_e32 v59, 31, v58
	v_ashrrev_i32_e32 v61, 31, v60
	v_ashrrev_i32_e32 v63, 31, v62
	v_ashrrev_i32_e32 v65, 31, v64
	v_ashrrev_i32_e32 v67, 31, v66
	v_ashrrev_i32_e32 v69, 31, v68
	v_lshl_add_u64 v[70:71], s[10:11], 1, v[0:1]
	v_lshlrev_b64 v[54:55], 11, v[54:55]
	v_lshlrev_b64 v[56:57], 11, v[56:57]
	v_lshlrev_b64 v[58:59], 11, v[58:59]
	v_lshlrev_b64 v[60:61], 11, v[60:61]
	v_lshlrev_b64 v[62:63], 11, v[62:63]
	v_lshlrev_b64 v[64:65], 11, v[64:65]
	v_lshlrev_b64 v[66:67], 11, v[66:67]
	v_lshlrev_b64 v[68:69], 11, v[68:69]
	v_lshl_add_u64 v[54:55], v[70:71], 0, v[54:55]
	v_lshl_add_u64 v[56:57], v[70:71], 0, v[56:57]
	v_lshl_add_u64 v[58:59], v[70:71], 0, v[58:59]
	v_lshl_add_u64 v[60:61], v[70:71], 0, v[60:61]
	v_lshl_add_u64 v[62:63], v[70:71], 0, v[62:63]
	v_lshl_add_u64 v[64:65], v[70:71], 0, v[64:65]
	v_lshl_add_u64 v[66:67], v[70:71], 0, v[66:67]
	v_lshl_add_u64 v[68:69], v[70:71], 0, v[68:69]
	s_branch .Lcv313_n1

; __device__ __forceinline__ bf16_t f2bf(float f) { unsigned u = __float_as_uint(f); u += 0x7FFFu + ((u >> 16) & 1u); return (bf16_t)(u >> 16); }
;     ...
;     for (int t_ = first; t_ < ntile * ((REP & 1) + 1); t_ += gridDim.x) { const int t = t_ % ntile;
;         const int r0 = (t / nkt) * 64, k0 = (t % nkt) * 64;
;         __syncthreads();
; #pragma unroll
;         for (int i = 0; i < 8; ++i) { const int kk = i * 8 + w; tile[kk * 65 + lane] = src(k0 + kk, r0 + lane); }
;         __syncthreads();
; #pragma unroll
;         for (int i = 0; i < 8; ++i) { const int j = i * 8 + w; Bt[(size_t)(r0 + j) * ld + k0 + lane] = f2bf(tile[lane * 65 + j]); }
; __device__ void convert_phase(unsigned char* smem, const Params& p, int l) {
;     ...
;       conv_tiles(tile, wt + W_QKV, 4608, 1024, 113, [=](int k, int r) { return gn[k] * wi[(size_t)k * INC + HYC + r]; }); }
.Lcv316_top:
	s_waitcnt vmcnt(31)
	v_mul_f32_e32 v13, v13, v39
	s_waitcnt vmcnt(30)
	v_mul_f32_e32 v30, v32, v40
	s_waitcnt vmcnt(29)
	v_mul_f32_e32 v31, v33, v41
	s_waitcnt vmcnt(28)
	v_mul_f32_e32 v32, v34, v42
	s_waitcnt vmcnt(27)
	v_mul_f32_e32 v33, v35, v43
	s_waitcnt vmcnt(26)
	v_mul_f32_e32 v34, v36, v44
	s_waitcnt vmcnt(25)
	v_mul_f32_e32 v35, v37, v45
	s_waitcnt vmcnt(24)
	v_mul_f32_e32 v36, v38, v46
	ds_write_b32 v12, v13
	ds_write_b32 v12, v30 offset:2080
	ds_write_b32 v12, v31 offset:4160
	ds_write_b32 v12, v32 offset:6240
	ds_write_b32 v12, v33 offset:8320
	ds_write_b32 v12, v34 offset:10400
	ds_write_b32 v12, v35 offset:12480
	ds_write_b32 v12, v36 offset:14560
	s_waitcnt lgkmcnt(0)
	s_barrier
	ds_read2_b32 v[30:31], v4 offset1:8
	ds_read2_b32 v[32:33], v4 offset0:16 offset1:24
	ds_read2_b32 v[34:35], v4 offset0:32 offset1:40
	ds_read2_b32 v[36:37], v4 offset0:48 offset1:56
	s_waitcnt lgkmcnt(3)
	v_bfe_u32 v13, v30, 16, 1
	v_bfe_u32 v38, v31, 16, 1
	s_waitcnt lgkmcnt(2)
	v_bfe_u32 v39, v32, 16, 1
	v_bfe_u32 v40, v33, 16, 1
	s_waitcnt lgkmcnt(1)
	v_bfe_u32 v41, v34, 16, 1
	v_bfe_u32 v42, v35, 16, 1
	s_waitcnt lgkmcnt(0)
	v_bfe_u32 v43, v36, 16, 1
	v_bfe_u32 v44, v37, 16, 1
	v_add3_u32 v13, v30, v13, s88
	v_add3_u32 v30, v31, v38, s88
	v_add3_u32 v31, v32, v39, s88
	v_add3_u32 v32, v33, v40, s88
	v_add3_u32 v33, v34, v41, s88
	v_add3_u32 v34, v35, v42, s88
	v_add3_u32 v35, v36, v43, s88
	v_add3_u32 v36, v37, v44, s88
	global_store_short_d16_hi v[14:15], v13, off
	global_store_short_d16_hi v[16:17], v30, off
	global_store_short_d16_hi v[18:19], v31, off
	global_store_short_d16_hi v[20:21], v32, off
	global_store_short_d16_hi v[22:23], v33, off
	global_store_short_d16_hi v[24:25], v34, off
	global_store_short_d16_hi v[26:27], v35, off
	global_store_short_d16_hi v[28:29], v36, off
	s_lshl_b32 s98, s5, 1
	s_add_i32 s98, s98, s18
	s_cmp_lt_i32 s98, 0x480
	s_cbranch_scc0 .Lcv316_s0
	s_mul_hi_i32 s10, s98, 0x38e38e39
	s_lshr_b32 s11, s10, 31
	s_ashr_i32 s10, s10, 8
	s_add_i32 s10, s10, s11
	s_mulk_i32 s10, 0x480
	s_sub_i32 s10, s98, s10
	s_sext_i32_i16 s11, s10
	s_bfe_u32 s11, s11, 0x4001b
	s_add_i32 s11, s10, s11
	s_sext_i32_i16 s19, s11
	s_and_b32 s11, s11, 0xfff0
	s_lshl_b32 s19, s19, 2
	s_sub_i32 s10, s10, s11
	s_and_b32 s11, s19, 0xffffffc0
	s_sext_i32_i16 s10, s10
	s_lshl_b32 s10, s10, 6
	v_or_b32_e32 v16, s11, v2
	v_mov_b64_e32 v[14:15], s[6:7]
	v_ashrrev_i32_e32 v17, 31, v16
	v_add_u32_e32 v18, s10, v3
	v_add_u32_e32 v13, s10, v5
	v_add_u32_e32 v24, s10, v6
	v_add_u32_e32 v26, s10, v7
	v_add_u32_e32 v28, s10, v8
	v_add_u32_e32 v30, s10, v9
	v_add_u32_e32 v32, s10, v10
	v_add_u32_e32 v34, s10, v11
	v_mad_i64_i32 v[20:21], s[20:21], v18, s94, v[14:15]
	v_lshlrev_b64 v[16:17], 2, v[16:17]
	v_mad_i64_i32 v[22:23], s[20:21], v13, s94, v[14:15]
	v_mad_i64_i32 v[24:25], s[20:21], v24, s94, v[14:15]
	v_mad_i64_i32 v[26:27], s[20:21], v26, s94, v[14:15]
	v_mad_i64_i32 v[28:29], s[20:21], v28, s94, v[14:15]
	v_mad_i64_i32 v[30:31], s[20:21], v30, s94, v[14:15]
	v_mad_i64_i32 v[32:33], s[20:21], v32, s94, v[14:15]
	v_mad_i64_i32 v[14:15], s[20:21], v34, s94, v[14:15]
	v_lshl_add_u64 v[20:21], v[20:21], 0, v[16:17]
	v_lshl_add_u64 v[22:23], v[22:23], 0, v[16:17]
	v_lshl_add_u64 v[24:25], v[24:25], 0, v[16:17]
	v_lshl_add_u64 v[26:27], v[26:27], 0, v[16:17]
	v_lshl_add_u64 v[28:29], v[28:29], 0, v[16:17]
	v_lshl_add_u64 v[30:31], v[30:31], 0, v[16:17]
	v_lshl_add_u64 v[32:33], v[32:33], 0, v[16:17]
	v_lshl_add_u64 v[14:15], v[14:15], 0, v[16:17]
	v_add_co_u32_e32 v16, vcc, s78, v20
	v_ashrrev_i32_e32 v19, 31, v18
	s_nop 0
	v_addc_co_u32_e32 v17, vcc, 0, v21, vcc
	v_add_co_u32_e32 v20, vcc, s78, v22
	v_lshl_add_u64 v[18:19], v[18:19], 2, s[8:9]
	s_nop 0
	v_addc_co_u32_e32 v21, vcc, 0, v23, vcc
	v_add_co_u32_e32 v22, vcc, s78, v24
	s_nop 1
	v_addc_co_u32_e32 v23, vcc, 0, v25, vcc
	v_add_co_u32_e32 v24, vcc, s78, v26
	s_nop 0
	v_addc_co_u32_e32 v25, vcc, 0, v27, vcc
	v_add_co_u32_e32 v26, vcc, s78, v28
	s_nop 1
	v_addc_co_u32_e32 v27, vcc, 0, v29, vcc
	v_add_co_u32_e32 v28, vcc, s78, v30
	s_nop 0
	v_addc_co_u32_e32 v29, vcc, 0, v31, vcc
	v_add_co_u32_e32 v30, vcc, s78, v32
	s_nop 1
	v_addc_co_u32_e32 v31, vcc, 0, v33, vcc
	v_add_co_u32_e32 v14, vcc, s78, v14
	global_load_dword v13, v[18:19], off
	global_load_dword v32, v[18:19], off offset:32
	global_load_dword v33, v[18:19], off offset:64
	global_load_dword v34, v[18:19], off offset:96
	global_load_dword v35, v[18:19], off offset:128
	global_load_dword v36, v[18:19], off offset:160
	global_load_dword v37, v[18:19], off offset:192
	global_load_dword v38, v[18:19], off offset:224
	v_addc_co_u32_e32 v15, vcc, 0, v15, vcc
	global_load_dword v39, v[16:17], off offset:2048
	global_load_dword v40, v[20:21], off offset:2048
	global_load_dword v41, v[22:23], off offset:2048
	global_load_dword v42, v[24:25], off offset:2048
	global_load_dword v43, v[26:27], off offset:2048
	global_load_dword v44, v[28:29], off offset:2048
	global_load_dword v45, v[30:31], off offset:2048
	global_load_dword v46, v[14:15], off offset:2048
	v_add_u32_e32 v14, s11, v3
	v_add_u32_e32 v16, s11, v5
	v_add_u32_e32 v18, s11, v6
	v_add_u32_e32 v20, s11, v7
	v_add_u32_e32 v22, s11, v8
	v_add_u32_e32 v24, s11, v9
	v_add_u32_e32 v26, s11, v10
	v_add_u32_e32 v28, s11, v11
	s_ashr_i32 s11, s10, 31
	v_ashrrev_i32_e32 v15, 31, v14
	v_ashrrev_i32_e32 v17, 31, v16
	v_ashrrev_i32_e32 v19, 31, v18
	v_ashrrev_i32_e32 v21, 31, v20
	v_ashrrev_i32_e32 v23, 31, v22
	v_ashrrev_i32_e32 v25, 31, v24
	v_ashrrev_i32_e32 v27, 31, v26
	v_ashrrev_i32_e32 v29, 31, v28
	v_lshl_add_u64 v[30:31], s[10:11], 1, v[0:1]
	v_lshlrev_b64 v[14:15], 11, v[14:15]
	v_lshlrev_b64 v[16:17], 11, v[16:17]
	v_lshlrev_b64 v[18:19], 11, v[18:19]
	v_lshlrev_b64 v[20:21], 11, v[20:21]
	v_lshlrev_b64 v[22:23], 11, v[22:23]
	v_lshlrev_b64 v[24:25], 11, v[24:25]
	v_lshlrev_b64 v[26:27], 11, v[26:27]
	v_lshlrev_b64 v[28:29], 11, v[28:29]
	v_lshl_add_u64 v[14:15], v[30:31], 0, v[14:15]
	v_lshl_add_u64 v[16:17], v[30:31], 0, v[16:17]
	v_lshl_add_u64 v[18:19], v[30:31], 0, v[18:19]
	v_lshl_add_u64 v[20:21], v[30:31], 0, v[20:21]
	v_lshl_add_u64 v[22:23], v[30:31], 0, v[22:23]
	v_lshl_add_u64 v[24:25], v[30:31], 0, v[24:25]
	v_lshl_add_u64 v[26:27], v[30:31], 0, v[26:27]
	v_lshl_add_u64 v[28:29], v[30:31], 0, v[28:29]
	s_branch .Lcv316_n0

; __device__ __forceinline__ bf16_t f2bf(float f) { unsigned u = __float_as_uint(f); u += 0x7FFFu + ((u >> 16) & 1u); return (bf16_t)(u >> 16); }
;     ...
;     for (int t_ = first; t_ < ntile * ((REP & 1) + 1); t_ += gridDim.x) { const int t = t_ % ntile;
;         const int r0 = (t / nkt) * 64, k0 = (t % nkt) * 64;
;         __syncthreads();
; #pragma unroll
;         for (int i = 0; i < 8; ++i) { const int kk = i * 8 + w; tile[kk * 65 + lane] = src(k0 + kk, r0 + lane); }
;         __syncthreads();
; #pragma unroll
;         for (int i = 0; i < 8; ++i) { const int j = i * 8 + w; Bt[(size_t)(r0 + j) * ld + k0 + lane] = f2bf(tile[lane * 65 + j]); }
; __device__ void convert_phase(unsigned char* smem, const Params& p, int l) {
;     ...
;       conv_tiles(tile, wt + W_QKV, 4608, 1024, 113, [=](int k, int r) { return gn[k] * wi[(size_t)k * INC + HYC + r]; }); }
.Lcv316_n0:
	s_add_i32 s18, s18, s5
	s_cmp_lt_i32 s18, 0x480
	s_cbranch_scc0 .LBB0_317
	s_waitcnt vmcnt(31)
	v_mul_f32_e32 v53, v53, v79
	s_waitcnt vmcnt(30)
	v_mul_f32_e32 v70, v72, v80
	s_waitcnt vmcnt(29)
	v_mul_f32_e32 v71, v73, v81
	s_waitcnt vmcnt(28)
	v_mul_f32_e32 v72, v74, v82
	s_waitcnt vmcnt(27)
	v_mul_f32_e32 v73, v75, v83
	s_waitcnt vmcnt(26)
	v_mul_f32_e32 v74, v76, v84
	s_waitcnt vmcnt(25)
	v_mul_f32_e32 v75, v77, v85
	s_waitcnt vmcnt(24)
	v_mul_f32_e32 v76, v78, v86
	ds_write_b32 v12, v53 offset:17408
	ds_write_b32 v12, v70 offset:19488
	ds_write_b32 v12, v71 offset:21568
	ds_write_b32 v12, v72 offset:23648
	ds_write_b32 v12, v73 offset:25728
	ds_write_b32 v12, v74 offset:27808
	ds_write_b32 v12, v75 offset:29888
	ds_write_b32 v12, v76 offset:31968
	s_waitcnt lgkmcnt(0)
	s_barrier
	ds_read2_b32 v[70:71], v95 offset1:8
	ds_read2_b32 v[72:73], v95 offset0:16 offset1:24
	ds_read2_b32 v[74:75], v95 offset0:32 offset1:40
	ds_read2_b32 v[76:77], v95 offset0:48 offset1:56
	s_waitcnt lgkmcnt(3)
	v_bfe_u32 v53, v70, 16, 1
	v_bfe_u32 v78, v71, 16, 1
	s_waitcnt lgkmcnt(2)
	v_bfe_u32 v79, v72, 16, 1
	v_bfe_u32 v80, v73, 16, 1
	s_waitcnt lgkmcnt(1)
	v_bfe_u32 v81, v74, 16, 1
	v_bfe_u32 v82, v75, 16, 1
	s_waitcnt lgkmcnt(0)
	v_bfe_u32 v83, v76, 16, 1
	v_bfe_u32 v84, v77, 16, 1
	v_add3_u32 v53, v70, v53, s88
	v_add3_u32 v70, v71, v78, s88
	v_add3_u32 v71, v72, v79, s88
	v_add3_u32 v72, v73, v80, s88
	v_add3_u32 v73, v74, v81, s88
	v_add3_u32 v74, v75, v82, s88
	v_add3_u32 v75, v76, v83, s88
	v_add3_u32 v76, v77, v84, s88
	global_store_short_d16_hi v[54:55], v53, off
	global_store_short_d16_hi v[56:57], v70, off
	global_store_short_d16_hi v[58:59], v71, off
	global_store_short_d16_hi v[60:61], v72, off
	global_store_short_d16_hi v[62:63], v73, off
	global_store_short_d16_hi v[64:65], v74, off
	global_store_short_d16_hi v[66:67], v75, off
	global_store_short_d16_hi v[68:69], v76, off
	s_lshl_b32 s98, s5, 1
	s_add_i32 s98, s98, s18
	s_cmp_lt_i32 s98, 0x480
	s_cbranch_scc0 .Lcv316_s1
	s_mul_hi_i32 s10, s98, 0x38e38e39
	s_lshr_b32 s11, s10, 31
	s_ashr_i32 s10, s10, 8
	s_add_i32 s10, s10, s11
	s_mulk_i32 s10, 0x480
	s_sub_i32 s10, s98, s10
	s_sext_i32_i16 s11, s10
	s_bfe_u32 s11, s11, 0x4001b
	s_add_i32 s11, s10, s11
	s_sext_i32_i16 s19, s11
	s_and_b32 s11, s11, 0xfff0
	s_lshl_b32 s19, s19, 2
	s_sub_i32 s10, s10, s11
	s_and_b32 s11, s19, 0xffffffc0
	s_sext_i32_i16 s10, s10
	s_lshl_b32 s10, s10, 6
	v_or_b32_e32 v56, s11, v2
	v_mov_b64_e32 v[54:55], s[6:7]
	v_ashrrev_i32_e32 v57, 31, v56
	v_add_u32_e32 v58, s10, v3
	v_add_u32_e32 v53, s10, v5
	v_add_u32_e32 v64, s10, v6
	v_add_u32_e32 v66, s10, v7
	v_add_u32_e32 v68, s10, v8
	v_add_u32_e32 v70, s10, v9
	v_add_u32_e32 v72, s10, v10
	v_add_u32_e32 v74, s10, v11
	v_mad_i64_i32 v[60:61], s[20:21], v58, s94, v[54:55]
	v_lshlrev_b64 v[56:57], 2, v[56:57]
	v_mad_i64_i32 v[62:63], s[20:21], v53, s94, v[54:55]
	v_mad_i64_i32 v[64:65], s[20:21], v64, s94, v[54:55]
	v_mad_i64_i32 v[66:67], s[20:21], v66, s94, v[54:55]
	v_mad_i64_i32 v[68:69], s[20:21], v68, s94, v[54:55]
	v_mad_i64_i32 v[70:71], s[20:21], v70, s94, v[54:55]
	v_mad_i64_i32 v[72:73], s[20:21], v72, s94, v[54:55]
	v_mad_i64_i32 v[54:55], s[20:21], v74, s94, v[54:55]
	v_lshl_add_u64 v[60:61], v[60:61], 0, v[56:57]
	v_lshl_add_u64 v[62:63], v[62:63], 0, v[56:57]
	v_lshl_add_u64 v[64:65], v[64:65], 0, v[56:57]
	v_lshl_add_u64 v[66:67], v[66:67], 0, v[56:57]
	v_lshl_add_u64 v[68:69], v[68:69], 0, v[56:57]
	v_lshl_add_u64 v[70:71], v[70:71], 0, v[56:57]
	v_lshl_add_u64 v[72:73], v[72:73], 0, v[56:57]
	v_lshl_add_u64 v[54:55], v[54:55], 0, v[56:57]
	v_add_co_u32_e32 v56, vcc, s78, v60
	v_ashrrev_i32_e32 v59, 31, v58
	s_nop 0
	v_addc_co_u32_e32 v57, vcc, 0, v61, vcc
	v_add_co_u32_e32 v60, vcc, s78, v62
	v_lshl_add_u64 v[58:59], v[58:59], 2, s[8:9]
	s_nop 0
	v_addc_co_u32_e32 v61, vcc, 0, v63, vcc
	v_add_co_u32_e32 v62, vcc, s78, v64
	s_nop 1
	v_addc_co_u32_e32 v63, vcc, 0, v65, vcc
	v_add_co_u32_e32 v64, vcc, s78, v66
	s_nop 0
	v_addc_co_u32_e32 v65, vcc, 0, v67, vcc
	v_add_co_u32_e32 v66, vcc, s78, v68
	s_nop 1
	v_addc_co_u32_e32 v67, vcc, 0, v69, vcc
	v_add_co_u32_e32 v68, vcc, s78, v70
	s_nop 0
	v_addc_co_u32_e32 v69, vcc, 0, v71, vcc
	v_add_co_u32_e32 v70, vcc, s78, v72
	s_nop 1
	v_addc_co_u32_e32 v71, vcc, 0, v73, vcc
	v_add_co_u32_e32 v54, vcc, s78, v54
	global_load_dword v53, v[58:59], off
	global_load_dword v72, v[58:59], off offset:32
	global_load_dword v73, v[58:59], off offset:64
	global_load_dword v74, v[58:59], off offset:96
	global_load_dword v75, v[58:59], off offset:128
	global_load_dword v76, v[58:59], off offset:160
	global_load_dword v77, v[58:59], off offset:192
	global_load_dword v78, v[58:59], off offset:224
	v_addc_co_u32_e32 v55, vcc, 0, v55, vcc
	global_load_dword v79, v[56:57], off offset:2048
	global_load_dword v80, v[60:61], off offset:2048
	global_load_dword v81, v[62:63], off offset:2048
	global_load_dword v82, v[64:65], off offset:2048
	global_load_dword v83, v[66:67], off offset:2048
	global_load_dword v84, v[68:69], off offset:2048
	global_load_dword v85, v[70:71], off offset:2048
	global_load_dword v86, v[54:55], off offset:2048
	v_add_u32_e32 v54, s11, v3
	v_add_u32_e32 v56, s11, v5
	v_add_u32_e32 v58, s11, v6
	v_add_u32_e32 v60, s11, v7
	v_add_u32_e32 v62, s11, v8
	v_add_u32_e32 v64, s11, v9
	v_add_u32_e32 v66, s11, v10
	v_add_u32_e32 v68, s11, v11
	s_ashr_i32 s11, s10, 31
	v_ashrrev_i32_e32 v55, 31, v54
	v_ashrrev_i32_e32 v57, 31, v56
	v_ashrrev_i32_e32 v59, 31, v58
	v_ashrrev_i32_e32 v61, 31, v60
	v_ashrrev_i32_e32 v63, 31, v62
	v_ashrrev_i32_e32 v65, 31, v64
	v_ashrrev_i32_e32 v67, 31, v66
	v_ashrrev_i32_e32 v69, 31, v68
	v_lshl_add_u64 v[70:71], s[10:11], 1, v[0:1]
	v_lshlrev_b64 v[54:55], 11, v[54:55]
	v_lshlrev_b64 v[56:57], 11, v[56:57]
	v_lshlrev_b64 v[58:59], 11, v[58:59]
	v_lshlrev_b64 v[60:61], 11, v[60:61]
	v_lshlrev_b64 v[62:63], 11, v[62:63]
	v_lshlrev_b64 v[64:65], 11, v[64:65]
	v_lshlrev_b64 v[66:67], 11, v[66:67]
	v_lshlrev_b64 v[68:69], 11, v[68:69]
	v_lshl_add_u64 v[54:55], v[70:71], 0, v[54:55]
	v_lshl_add_u64 v[56:57], v[70:71], 0, v[56:57]
	v_lshl_add_u64 v[58:59], v[70:71], 0, v[58:59]
	v_lshl_add_u64 v[60:61], v[70:71], 0, v[60:61]
	v_lshl_add_u64 v[62:63], v[70:71], 0, v[62:63]
	v_lshl_add_u64 v[64:65], v[70:71], 0, v[64:65]
	v_lshl_add_u64 v[66:67], v[70:71], 0, v[66:67]
	v_lshl_add_u64 v[68:69], v[70:71], 0, v[68:69]
	s_branch .Lcv316_n1

; __device__ __forceinline__ bf16_t f2bf(float f) { unsigned u = __float_as_uint(f); u += 0x7FFFu + ((u >> 16) & 1u); return (bf16_t)(u >> 16); }
;     ...
;     for (int t_ = first; t_ < ntile * ((REP & 1) + 1); t_ += gridDim.x) { const int t = t_ % ntile;
;         const int r0 = (t / nkt) * 64, k0 = (t % nkt) * 64;
;         __syncthreads();
; #pragma unroll
;         for (int i = 0; i < 8; ++i) { const int kk = i * 8 + w; tile[kk * 65 + lane] = src(k0 + kk, r0 + lane); }
;         __syncthreads();
; #pragma unroll
;         for (int i = 0; i < 8; ++i) { const int j = i * 8 + w; Bt[(size_t)(r0 + j) * ld + k0 + lane] = f2bf(tile[lane * 65 + j]); }
; __device__ void convert_phase(unsigned char* smem, const Params& p, int l) {
;     ...
;     { const float* wgt = ((const float*)ldp(26)) + (size_t)l * DM * 3072; const float* gn = ((const float*)ldp(5)) + l * DM; conv_tiles(tile, wt + W_GATE, 3072, 1024, 151, [=](int k, int r) { return gn[k] * wgt[(size_t)k * 3072 + r]; }); }
.Lcv319_top:
	s_waitcnt vmcnt(31)
	v_mul_f32_e32 v13, v13, v39
	s_waitcnt vmcnt(30)
	v_mul_f32_e32 v30, v32, v40
	s_waitcnt vmcnt(29)
	v_mul_f32_e32 v31, v33, v41
	s_waitcnt vmcnt(28)
	v_mul_f32_e32 v32, v34, v42
	s_waitcnt vmcnt(27)
	v_mul_f32_e32 v33, v35, v43
	s_waitcnt vmcnt(26)
	v_mul_f32_e32 v34, v36, v44
	s_waitcnt vmcnt(25)
	v_mul_f32_e32 v35, v37, v45
	s_waitcnt vmcnt(24)
	v_mul_f32_e32 v36, v38, v46
	ds_write_b32 v12, v13
	ds_write_b32 v12, v30 offset:2080
	ds_write_b32 v12, v31 offset:4160
	ds_write_b32 v12, v32 offset:6240
	ds_write_b32 v12, v33 offset:8320
	ds_write_b32 v12, v34 offset:10400
	ds_write_b32 v12, v35 offset:12480
	ds_write_b32 v12, v36 offset:14560
	s_waitcnt lgkmcnt(0)
	s_barrier
	ds_read2_b32 v[30:31], v4 offset1:8
	ds_read2_b32 v[32:33], v4 offset0:16 offset1:24
	ds_read2_b32 v[34:35], v4 offset0:32 offset1:40
	ds_read2_b32 v[36:37], v4 offset0:48 offset1:56
	s_waitcnt lgkmcnt(3)
	v_bfe_u32 v13, v30, 16, 1
	v_bfe_u32 v38, v31, 16, 1
	s_waitcnt lgkmcnt(2)
	v_bfe_u32 v39, v32, 16, 1
	v_bfe_u32 v40, v33, 16, 1
	s_waitcnt lgkmcnt(1)
	v_bfe_u32 v41, v34, 16, 1
	v_bfe_u32 v42, v35, 16, 1
	s_waitcnt lgkmcnt(0)
	v_bfe_u32 v43, v36, 16, 1
	v_bfe_u32 v44, v37, 16, 1
	v_add3_u32 v13, v30, v13, s88
	v_add3_u32 v30, v31, v38, s88
	v_add3_u32 v31, v32, v39, s88
	v_add3_u32 v32, v33, v40, s88
	v_add3_u32 v33, v34, v41, s88
	v_add3_u32 v34, v35, v42, s88
	v_add3_u32 v35, v36, v43, s88
	v_add3_u32 v36, v37, v44, s88
	global_store_short_d16_hi v[14:15], v13, off
	global_store_short_d16_hi v[16:17], v30, off
	global_store_short_d16_hi v[18:19], v31, off
	global_store_short_d16_hi v[20:21], v32, off
	global_store_short_d16_hi v[22:23], v33, off
	global_store_short_d16_hi v[24:25], v34, off
	global_store_short_d16_hi v[26:27], v35, off
	global_store_short_d16_hi v[28:29], v36, off
	s_lshl_b32 s98, s5, 1
	s_add_i32 s98, s98, s17
	s_cmp_lt_i32 s98, 0x300
	s_cbranch_scc0 .Lcv319_s0
	s_mul_hi_i32 s10, s98, 0x2aaaaaab
	s_lshr_b32 s11, s10, 31
	s_lshr_b32 s10, s10, 7
	s_add_i32 s10, s10, s11
	s_mulk_i32 s10, 0x300
	s_sub_i32 s10, s98, s10
	s_sext_i32_i16 s11, s10
	s_bfe_u32 s11, s11, 0x4001b
	s_add_i32 s11, s10, s11
	s_sext_i32_i16 s18, s11
	s_and_b32 s11, s11, 0xfff0
	s_sub_i32 s10, s10, s11
	s_lshl_b32 s18, s18, 2
	s_sext_i32_i16 s10, s10
	s_and_b32 s11, s18, 0xffffffc0
	s_lshl_b32 s10, s10, 6
	v_or_b32_e32 v14, s11, v2
	v_add_u32_e32 v16, s10, v3
	v_ashrrev_i32_e32 v15, 31, v14
	v_ashrrev_i32_e32 v17, 31, v16
	v_add_u32_e32 v13, s10, v5
	v_add_u32_e32 v22, s10, v6
	v_add_u32_e32 v24, s10, v7
	v_add_u32_e32 v26, s10, v8
	v_add_u32_e32 v28, s10, v9
	v_add_u32_e32 v30, s10, v10
	v_add_u32_e32 v32, s10, v11
	v_lshl_add_u64 v[14:15], v[14:15], 2, s[6:7]
	v_lshl_add_u64 v[18:19], v[16:17], 2, s[8:9]
	v_mad_i64_i32 v[16:17], s[18:19], v16, s79, v[14:15]
	v_mad_i64_i32 v[20:21], s[18:19], v13, s79, v[14:15]
	v_mad_i64_i32 v[22:23], s[18:19], v22, s79, v[14:15]
	v_mad_i64_i32 v[24:25], s[18:19], v24, s79, v[14:15]
	v_mad_i64_i32 v[26:27], s[18:19], v26, s79, v[14:15]
	v_mad_i64_i32 v[28:29], s[18:19], v28, s79, v[14:15]
	v_mad_i64_i32 v[30:31], s[18:19], v30, s79, v[14:15]
	v_mad_i64_i32 v[14:15], s[18:19], v32, s79, v[14:15]
	global_load_dword v13, v[18:19], off
	global_load_dword v32, v[18:19], off offset:32
	global_load_dword v33, v[18:19], off offset:64
	global_load_dword v34, v[18:19], off offset:96
	global_load_dword v35, v[18:19], off offset:128
	global_load_dword v36, v[18:19], off offset:160
	global_load_dword v37, v[18:19], off offset:192
	global_load_dword v38, v[18:19], off offset:224
	global_load_dword v39, v[16:17], off
	global_load_dword v40, v[20:21], off
	global_load_dword v41, v[22:23], off
	global_load_dword v42, v[24:25], off
	global_load_dword v43, v[26:27], off
	global_load_dword v44, v[28:29], off
	global_load_dword v45, v[30:31], off
	global_load_dword v46, v[14:15], off
	v_add_u32_e32 v14, s11, v3
	v_add_u32_e32 v16, s11, v5
	v_add_u32_e32 v18, s11, v6
	v_add_u32_e32 v20, s11, v7
	v_add_u32_e32 v22, s11, v8
	v_add_u32_e32 v24, s11, v9
	v_add_u32_e32 v26, s11, v10
	v_add_u32_e32 v28, s11, v11
	s_ashr_i32 s11, s10, 31
	v_ashrrev_i32_e32 v15, 31, v14
	v_ashrrev_i32_e32 v17, 31, v16
	v_ashrrev_i32_e32 v19, 31, v18
	v_ashrrev_i32_e32 v21, 31, v20
	v_ashrrev_i32_e32 v23, 31, v22
	v_ashrrev_i32_e32 v25, 31, v24
	v_ashrrev_i32_e32 v27, 31, v26
	v_ashrrev_i32_e32 v29, 31, v28
	v_lshl_add_u64 v[30:31], s[10:11], 1, v[0:1]
	v_lshlrev_b64 v[14:15], 11, v[14:15]
	v_lshlrev_b64 v[16:17], 11, v[16:17]
	v_lshlrev_b64 v[18:19], 11, v[18:19]
	v_lshlrev_b64 v[20:21], 11, v[20:21]
	v_lshlrev_b64 v[22:23], 11, v[22:23]
	v_lshlrev_b64 v[24:25], 11, v[24:25]
	v_lshlrev_b64 v[26:27], 11, v[26:27]
	v_lshlrev_b64 v[28:29], 11, v[28:29]
	v_lshl_add_u64 v[14:15], v[30:31], 0, v[14:15]
	v_lshl_add_u64 v[16:17], v[30:31], 0, v[16:17]
	v_lshl_add_u64 v[18:19], v[30:31], 0, v[18:19]
	v_lshl_add_u64 v[20:21], v[30:31], 0, v[20:21]
	v_lshl_add_u64 v[22:23], v[30:31], 0, v[22:23]
	v_lshl_add_u64 v[24:25], v[30:31], 0, v[24:25]
	v_lshl_add_u64 v[26:27], v[30:31], 0, v[26:27]
	v_lshl_add_u64 v[28:29], v[30:31], 0, v[28:29]
	s_branch .Lcv319_n0

; __device__ __forceinline__ bf16_t f2bf(float f) { unsigned u = __float_as_uint(f); u += 0x7FFFu + ((u >> 16) & 1u); return (bf16_t)(u >> 16); }
;     ...
;     for (int t_ = first; t_ < ntile * ((REP & 1) + 1); t_ += gridDim.x) { const int t = t_ % ntile;
;         const int r0 = (t / nkt) * 64, k0 = (t % nkt) * 64;
;         __syncthreads();
; #pragma unroll
;         for (int i = 0; i < 8; ++i) { const int kk = i * 8 + w; tile[kk * 65 + lane] = src(k0 + kk, r0 + lane); }
;         __syncthreads();
; #pragma unroll
;         for (int i = 0; i < 8; ++i) { const int j = i * 8 + w; Bt[(size_t)(r0 + j) * ld + k0 + lane] = f2bf(tile[lane * 65 + j]); }
; __device__ void convert_phase(unsigned char* smem, const Params& p, int l) {
;     ...
;     { const float* wgt = ((const float*)ldp(26)) + (size_t)l * DM * 3072; const float* gn = ((const float*)ldp(5)) + l * DM; conv_tiles(tile, wt + W_GATE, 3072, 1024, 151, [=](int k, int r) { return gn[k] * wgt[(size_t)k * 3072 + r]; }); }
.Lcv319_n0:
	s_add_i32 s17, s17, s5
	s_cmp_lt_i32 s17, 0x300
	s_cbranch_scc0 .LBB0_320
	s_waitcnt vmcnt(31)
	v_mul_f32_e32 v53, v53, v79
	s_waitcnt vmcnt(30)
	v_mul_f32_e32 v70, v72, v80
	s_waitcnt vmcnt(29)
	v_mul_f32_e32 v71, v73, v81
	s_waitcnt vmcnt(28)
	v_mul_f32_e32 v72, v74, v82
	s_waitcnt vmcnt(27)
	v_mul_f32_e32 v73, v75, v83
	s_waitcnt vmcnt(26)
	v_mul_f32_e32 v74, v76, v84
	s_waitcnt vmcnt(25)
	v_mul_f32_e32 v75, v77, v85
	s_waitcnt vmcnt(24)
	v_mul_f32_e32 v76, v78, v86
	ds_write_b32 v12, v53 offset:17408
	ds_write_b32 v12, v70 offset:19488
	ds_write_b32 v12, v71 offset:21568
	ds_write_b32 v12, v72 offset:23648
	ds_write_b32 v12, v73 offset:25728
	ds_write_b32 v12, v74 offset:27808
	ds_write_b32 v12, v75 offset:29888
	ds_write_b32 v12, v76 offset:31968
	s_waitcnt lgkmcnt(0)
	s_barrier
	ds_read2_b32 v[70:71], v95 offset1:8
	ds_read2_b32 v[72:73], v95 offset0:16 offset1:24
	ds_read2_b32 v[74:75], v95 offset0:32 offset1:40
	ds_read2_b32 v[76:77], v95 offset0:48 offset1:56
	s_waitcnt lgkmcnt(3)
	v_bfe_u32 v53, v70, 16, 1
	v_bfe_u32 v78, v71, 16, 1
	s_waitcnt lgkmcnt(2)
	v_bfe_u32 v79, v72, 16, 1
	v_bfe_u32 v80, v73, 16, 1
	s_waitcnt lgkmcnt(1)
	v_bfe_u32 v81, v74, 16, 1
	v_bfe_u32 v82, v75, 16, 1
	s_waitcnt lgkmcnt(0)
	v_bfe_u32 v83, v76, 16, 1
	v_bfe_u32 v84, v77, 16, 1
	v_add3_u32 v53, v70, v53, s88
	v_add3_u32 v70, v71, v78, s88
	v_add3_u32 v71, v72, v79, s88
	v_add3_u32 v72, v73, v80, s88
	v_add3_u32 v73, v74, v81, s88
	v_add3_u32 v74, v75, v82, s88
	v_add3_u32 v75, v76, v83, s88
	v_add3_u32 v76, v77, v84, s88
	global_store_short_d16_hi v[54:55], v53, off
	global_store_short_d16_hi v[56:57], v70, off
	global_store_short_d16_hi v[58:59], v71, off
	global_store_short_d16_hi v[60:61], v72, off
	global_store_short_d16_hi v[62:63], v73, off
	global_store_short_d16_hi v[64:65], v74, off
	global_store_short_d16_hi v[66:67], v75, off
	global_store_short_d16_hi v[68:69], v76, off
	s_lshl_b32 s98, s5, 1
	s_add_i32 s98, s98, s17
	s_cmp_lt_i32 s98, 0x300
	s_cbranch_scc0 .Lcv319_s1
	s_mul_hi_i32 s10, s98, 0x2aaaaaab
	s_lshr_b32 s11, s10, 31
	s_lshr_b32 s10, s10, 7
	s_add_i32 s10, s10, s11
	s_mulk_i32 s10, 0x300
	s_sub_i32 s10, s98, s10
	s_sext_i32_i16 s11, s10
	s_bfe_u32 s11, s11, 0x4001b
	s_add_i32 s11, s10, s11
	s_sext_i32_i16 s18, s11
	s_and_b32 s11, s11, 0xfff0
	s_sub_i32 s10, s10, s11
	s_lshl_b32 s18, s18, 2
	s_sext_i32_i16 s10, s10
	s_and_b32 s11, s18, 0xffffffc0
	s_lshl_b32 s10, s10, 6
	v_or_b32_e32 v54, s11, v2
	v_add_u32_e32 v56, s10, v3
	v_ashrrev_i32_e32 v55, 31, v54
	v_ashrrev_i32_e32 v57, 31, v56
	v_add_u32_e32 v53, s10, v5
	v_add_u32_e32 v62, s10, v6
	v_add_u32_e32 v64, s10, v7
	v_add_u32_e32 v66, s10, v8
	v_add_u32_e32 v68, s10, v9
	v_add_u32_e32 v70, s10, v10
	v_add_u32_e32 v72, s10, v11
	v_lshl_add_u64 v[54:55], v[54:55], 2, s[6:7]
	v_lshl_add_u64 v[58:59], v[56:57], 2, s[8:9]
	v_mad_i64_i32 v[56:57], s[18:19], v56, s79, v[54:55]
	v_mad_i64_i32 v[60:61], s[18:19], v53, s79, v[54:55]
	v_mad_i64_i32 v[62:63], s[18:19], v62, s79, v[54:55]
	v_mad_i64_i32 v[64:65], s[18:19], v64, s79, v[54:55]
	v_mad_i64_i32 v[66:67], s[18:19], v66, s79, v[54:55]
	v_mad_i64_i32 v[68:69], s[18:19], v68, s79, v[54:55]
	v_mad_i64_i32 v[70:71], s[18:19], v70, s79, v[54:55]
	v_mad_i64_i32 v[54:55], s[18:19], v72, s79, v[54:55]
	global_load_dword v53, v[58:59], off
	global_load_dword v72, v[58:59], off offset:32
	global_load_dword v73, v[58:59], off offset:64
	global_load_dword v74, v[58:59], off offset:96
	global_load_dword v75, v[58:59], off offset:128
	global_load_dword v76, v[58:59], off offset:160
	global_load_dword v77, v[58:59], off offset:192
	global_load_dword v78, v[58:59], off offset:224
	global_load_dword v79, v[56:57], off
	global_load_dword v80, v[60:61], off
	global_load_dword v81, v[62:63], off
	global_load_dword v82, v[64:65], off
	global_load_dword v83, v[66:67], off
	global_load_dword v84, v[68:69], off
	global_load_dword v85, v[70:71], off
	global_load_dword v86, v[54:55], off
	v_add_u32_e32 v54, s11, v3
	v_add_u32_e32 v56, s11, v5
	v_add_u32_e32 v58, s11, v6
	v_add_u32_e32 v60, s11, v7
	v_add_u32_e32 v62, s11, v8
	v_add_u32_e32 v64, s11, v9
	v_add_u32_e32 v66, s11, v10
	v_add_u32_e32 v68, s11, v11
	s_ashr_i32 s11, s10, 31
	v_ashrrev_i32_e32 v55, 31, v54
	v_ashrrev_i32_e32 v57, 31, v56
	v_ashrrev_i32_e32 v59, 31, v58
	v_ashrrev_i32_e32 v61, 31, v60
	v_ashrrev_i32_e32 v63, 31, v62
	v_ashrrev_i32_e32 v65, 31, v64
	v_ashrrev_i32_e32 v67, 31, v66
	v_ashrrev_i32_e32 v69, 31, v68
	v_lshl_add_u64 v[70:71], s[10:11], 1, v[0:1]
	v_lshlrev_b64 v[54:55], 11, v[54:55]
	v_lshlrev_b64 v[56:57], 11, v[56:57]
	v_lshlrev_b64 v[58:59], 11, v[58:59]
	v_lshlrev_b64 v[60:61], 11, v[60:61]
	v_lshlrev_b64 v[62:63], 11, v[62:63]
	v_lshlrev_b64 v[64:65], 11, v[64:65]
	v_lshlrev_b64 v[66:67], 11, v[66:67]
	v_lshlrev_b64 v[68:69], 11, v[68:69]
	v_lshl_add_u64 v[54:55], v[70:71], 0, v[54:55]
	v_lshl_add_u64 v[56:57], v[70:71], 0, v[56:57]
	v_lshl_add_u64 v[58:59], v[70:71], 0, v[58:59]
	v_lshl_add_u64 v[60:61], v[70:71], 0, v[60:61]
	v_lshl_add_u64 v[62:63], v[70:71], 0, v[62:63]
	v_lshl_add_u64 v[64:65], v[70:71], 0, v[64:65]
	v_lshl_add_u64 v[66:67], v[70:71], 0, v[66:67]
	v_lshl_add_u64 v[68:69], v[70:71], 0, v[68:69]
	s_branch .Lcv319_n1

; __device__ __forceinline__ bf16_t f2bf(float f) { unsigned u = __float_as_uint(f); u += 0x7FFFu + ((u >> 16) & 1u); return (bf16_t)(u >> 16); }
;     ...
;     for (int t_ = first; t_ < ntile * ((REP & 1) + 1); t_ += gridDim.x) { const int t = t_ % ntile;
;         const int r0 = (t / nkt) * 64, k0 = (t % nkt) * 64;
;         __syncthreads();
; #pragma unroll
;         for (int i = 0; i < 8; ++i) { const int kk = i * 8 + w; tile[kk * 65 + lane] = src(k0 + kk, r0 + lane); }
;         __syncthreads();
; #pragma unroll
;         for (int i = 0; i < 8; ++i) { const int j = i * 8 + w; Bt[(size_t)(r0 + j) * ld + k0 + lane] = f2bf(tile[lane * 65 + j]); }
; __device__ void convert_phase(unsigned char* smem, const Params& p, int l) {
;     ...
;     { const float* wg = ((const float*)ldp(33)) + uo; const float* wu = ((const float*)ldp(34)) + uo; const float* gn = ((const float*)ldp(32)) + l * DM;
;       conv_tiles(tile, wt + W_UP2, 5632, 1024, 53, [=](int k, int r) { const int col = (r >> 5) * 16 + (r & 15); return gn[k] * (((r >> 4) & 1) ? wu[(size_t)k * DFF + col] : wg[(size_t)k * DFF + col]); }); }
.Lcv334_top:
	s_waitcnt vmcnt(31)
	v_mul_f32_e32 v32, v34, v42
	s_waitcnt vmcnt(30)
	v_mul_f32_e32 v33, v35, v43
	s_waitcnt vmcnt(29)
	v_mul_f32_e32 v34, v36, v44
	s_waitcnt vmcnt(28)
	v_mul_f32_e32 v35, v37, v45
	s_waitcnt vmcnt(27)
	v_mul_f32_e32 v36, v38, v46
	s_waitcnt vmcnt(26)
	v_mul_f32_e32 v37, v39, v47
	s_waitcnt vmcnt(25)
	v_mul_f32_e32 v38, v40, v48
	s_waitcnt vmcnt(24)
	v_mul_f32_e32 v39, v41, v49
	ds_write_b32 v15, v32
	ds_write_b32 v15, v33 offset:2080
	ds_write_b32 v15, v34 offset:4160
	ds_write_b32 v15, v35 offset:6240
	ds_write_b32 v15, v36 offset:8320
	ds_write_b32 v15, v37 offset:10400
	ds_write_b32 v15, v38 offset:12480
	ds_write_b32 v15, v39 offset:14560
	s_waitcnt lgkmcnt(0)
	s_barrier
	ds_read2_b32 v[32:33], v7 offset1:8
	ds_read2_b32 v[34:35], v7 offset0:16 offset1:24
	ds_read2_b32 v[36:37], v7 offset0:32 offset1:40
	ds_read2_b32 v[38:39], v7 offset0:48 offset1:56
	s_waitcnt lgkmcnt(3)
	v_bfe_u32 v40, v32, 16, 1
	v_bfe_u32 v41, v33, 16, 1
	s_waitcnt lgkmcnt(2)
	v_bfe_u32 v42, v34, 16, 1
	v_bfe_u32 v43, v35, 16, 1
	s_waitcnt lgkmcnt(1)
	v_bfe_u32 v44, v36, 16, 1
	v_bfe_u32 v45, v37, 16, 1
	s_waitcnt lgkmcnt(0)
	v_bfe_u32 v46, v38, 16, 1
	v_bfe_u32 v47, v39, 16, 1
	v_add3_u32 v32, v32, v40, s88
	v_add3_u32 v33, v33, v41, s88
	v_add3_u32 v34, v34, v42, s88
	v_add3_u32 v35, v35, v43, s88
	v_add3_u32 v36, v36, v44, s88
	v_add3_u32 v37, v37, v45, s88
	v_add3_u32 v38, v38, v46, s88
	v_add3_u32 v39, v39, v47, s88
	global_store_short_d16_hi v[16:17], v32, off
	global_store_short_d16_hi v[18:19], v33, off
	global_store_short_d16_hi v[20:21], v34, off
	global_store_short_d16_hi v[22:23], v35, off
	global_store_short_d16_hi v[24:25], v36, off
	global_store_short_d16_hi v[26:27], v37, off
	global_store_short_d16_hi v[28:29], v38, off
	global_store_short_d16_hi v[30:31], v39, off
	s_lshl_b32 s98, s5, 1
	s_add_i32 s98, s98, s10
	s_cmp_lt_i32 s98, 0x580
	s_cbranch_scc0 .Lcv334_s0
	s_mul_hi_i32 s8, s98, 0x2e8ba2e9
	s_lshr_b32 s9, s8, 31
	s_ashr_i32 s8, s8, 8
	s_add_i32 s8, s8, s9
	s_mulk_i32 s8, 0x580
	s_sub_i32 s8, s98, s8
	s_sext_i32_i16 s9, s8
	s_bfe_u32 s9, s9, 0x4001b
	s_add_i32 s9, s8, s9
	s_sext_i32_i16 s11, s9
	s_lshl_b32 s11, s11, 2
	s_and_b32 s9, s9, 0xfff0
	s_andn2_b32 s11, s11, 63
	s_sub_i32 s8, s8, s9
	v_or_b32_e32 v16, s11, v4
	s_sext_i32_i16 s8, s8
	v_ashrrev_i32_e32 v17, 1, v16
	s_lshl_b32 s8, s8, 6
	v_and_or_b32 v18, v17, -16, v6
	v_add_u32_e32 v16, s8, v5
	v_ashrrev_i32_e32 v19, 31, v18
	v_ashrrev_i32_e32 v17, 31, v16
	v_lshl_add_u64 v[18:19], v[18:19], 2, v[0:1]
	v_add_u32_e32 v22, s8, v8
	v_add_u32_e32 v23, s8, v9
	v_add_u32_e32 v24, s8, v10
	v_add_u32_e32 v26, s8, v11
	v_add_u32_e32 v28, s8, v12
	v_add_u32_e32 v30, s8, v13
	v_add_u32_e32 v32, s8, v14
	v_lshl_add_u64 v[20:21], v[16:17], 2, s[6:7]
	v_mad_i64_i32 v[16:17], s[16:17], v16, s33, v[18:19]
	global_load_dword v34, v[20:21], off
	global_load_dword v35, v[20:21], off offset:32
	global_load_dword v36, v[20:21], off offset:64
	global_load_dword v37, v[20:21], off offset:96
	global_load_dword v38, v[20:21], off offset:128
	global_load_dword v39, v[20:21], off offset:160
	global_load_dword v40, v[20:21], off offset:192
	global_load_dword v41, v[20:21], off offset:224
	v_mad_i64_i32 v[20:21], s[16:17], v22, s33, v[18:19]
	v_mad_i64_i32 v[22:23], s[16:17], v23, s33, v[18:19]
	v_mad_i64_i32 v[24:25], s[16:17], v24, s33, v[18:19]
	v_mad_i64_i32 v[26:27], s[16:17], v26, s33, v[18:19]
	v_mad_i64_i32 v[28:29], s[16:17], v28, s33, v[18:19]
	v_mad_i64_i32 v[30:31], s[16:17], v30, s33, v[18:19]
	v_mad_i64_i32 v[18:19], s[16:17], v32, s33, v[18:19]
	global_load_dword v42, v[16:17], off
	global_load_dword v43, v[20:21], off
	global_load_dword v44, v[22:23], off
	global_load_dword v45, v[24:25], off
	global_load_dword v46, v[26:27], off
	global_load_dword v47, v[28:29], off
	global_load_dword v48, v[30:31], off
	global_load_dword v49, v[18:19], off
	v_add_u32_e32 v16, s11, v5
	v_add_u32_e32 v18, s11, v8
	v_add_u32_e32 v20, s11, v9
	v_add_u32_e32 v22, s11, v10
	v_add_u32_e32 v24, s11, v11
	v_add_u32_e32 v26, s11, v12
	v_add_u32_e32 v28, s11, v13
	v_add_u32_e32 v30, s11, v14
	s_ashr_i32 s9, s8, 31
	v_ashrrev_i32_e32 v17, 31, v16
	v_ashrrev_i32_e32 v19, 31, v18
	v_ashrrev_i32_e32 v21, 31, v20
	v_ashrrev_i32_e32 v23, 31, v22
	v_ashrrev_i32_e32 v25, 31, v24
	v_ashrrev_i32_e32 v27, 31, v26
	v_ashrrev_i32_e32 v29, 31, v28
	v_ashrrev_i32_e32 v31, 31, v30
	v_lshl_add_u64 v[32:33], s[8:9], 1, v[2:3]
	v_lshlrev_b64 v[16:17], 11, v[16:17]
	v_lshlrev_b64 v[18:19], 11, v[18:19]
	v_lshlrev_b64 v[20:21], 11, v[20:21]
	v_lshlrev_b64 v[22:23], 11, v[22:23]
	v_lshlrev_b64 v[24:25], 11, v[24:25]
	v_lshlrev_b64 v[26:27], 11, v[26:27]
	v_lshlrev_b64 v[28:29], 11, v[28:29]
	v_lshlrev_b64 v[30:31], 11, v[30:31]
	v_lshl_add_u64 v[16:17], v[32:33], 0, v[16:17]
	v_lshl_add_u64 v[18:19], v[32:33], 0, v[18:19]
	v_lshl_add_u64 v[20:21], v[32:33], 0, v[20:21]
	v_lshl_add_u64 v[22:23], v[32:33], 0, v[22:23]
	v_lshl_add_u64 v[24:25], v[32:33], 0, v[24:25]
	v_lshl_add_u64 v[26:27], v[32:33], 0, v[26:27]
	v_lshl_add_u64 v[28:29], v[32:33], 0, v[28:29]
	v_lshl_add_u64 v[30:31], v[32:33], 0, v[30:31]
	s_branch .Lcv334_n0

; __device__ __forceinline__ bf16_t f2bf(float f) { unsigned u = __float_as_uint(f); u += 0x7FFFu + ((u >> 16) & 1u); return (bf16_t)(u >> 16); }
;     ...
;     for (int t_ = first; t_ < ntile * ((REP & 1) + 1); t_ += gridDim.x) { const int t = t_ % ntile;
;         const int r0 = (t / nkt) * 64, k0 = (t % nkt) * 64;
;         __syncthreads();
; #pragma unroll
;         for (int i = 0; i < 8; ++i) { const int kk = i * 8 + w; tile[kk * 65 + lane] = src(k0 + kk, r0 + lane); }
;         __syncthreads();
; #pragma unroll
;         for (int i = 0; i < 8; ++i) { const int j = i * 8 + w; Bt[(size_t)(r0 + j) * ld + k0 + lane] = f2bf(tile[lane * 65 + j]); }
; __device__ void convert_phase(unsigned char* smem, const Params& p, int l) {
;     ...
;     { const float* wg = ((const float*)ldp(33)) + uo; const float* wu = ((const float*)ldp(34)) + uo; const float* gn = ((const float*)ldp(32)) + l * DM;
;       conv_tiles(tile, wt + W_UP2, 5632, 1024, 53, [=](int k, int r) { const int col = (r >> 5) * 16 + (r & 15); return gn[k] * (((r >> 4) & 1) ? wu[(size_t)k * DFF + col] : wg[(size_t)k * DFF + col]); }); }
.Lcv334_n0:
	s_add_i32 s10, s10, s5
	s_cmp_lt_i32 s10, 0x580
	s_cbranch_scc0 .LBB0_335
	s_waitcnt vmcnt(31)
	v_mul_f32_e32 v72, v74, v82
	s_waitcnt vmcnt(30)
	v_mul_f32_e32 v73, v75, v83
	s_waitcnt vmcnt(29)
	v_mul_f32_e32 v74, v76, v84
	s_waitcnt vmcnt(28)
	v_mul_f32_e32 v75, v77, v85
	s_waitcnt vmcnt(27)
	v_mul_f32_e32 v76, v78, v86
	s_waitcnt vmcnt(26)
	v_mul_f32_e32 v77, v79, v87
	s_waitcnt vmcnt(25)
	v_mul_f32_e32 v78, v80, v88
	s_waitcnt vmcnt(24)
	v_mul_f32_e32 v79, v81, v89
	ds_write_b32 v15, v72 offset:17408
	ds_write_b32 v15, v73 offset:19488
	ds_write_b32 v15, v74 offset:21568
	ds_write_b32 v15, v75 offset:23648
	ds_write_b32 v15, v76 offset:25728
	ds_write_b32 v15, v77 offset:27808
	ds_write_b32 v15, v78 offset:29888
	ds_write_b32 v15, v79 offset:31968
	s_waitcnt lgkmcnt(0)
	s_barrier
	ds_read2_b32 v[72:73], v95 offset1:8
	ds_read2_b32 v[74:75], v95 offset0:16 offset1:24
	ds_read2_b32 v[76:77], v95 offset0:32 offset1:40
	ds_read2_b32 v[78:79], v95 offset0:48 offset1:56
	s_waitcnt lgkmcnt(3)
	v_bfe_u32 v80, v72, 16, 1
	v_bfe_u32 v81, v73, 16, 1
	s_waitcnt lgkmcnt(2)
	v_bfe_u32 v82, v74, 16, 1
	v_bfe_u32 v83, v75, 16, 1
	s_waitcnt lgkmcnt(1)
	v_bfe_u32 v84, v76, 16, 1
	v_bfe_u32 v85, v77, 16, 1
	s_waitcnt lgkmcnt(0)
	v_bfe_u32 v86, v78, 16, 1
	v_bfe_u32 v87, v79, 16, 1
	v_add3_u32 v72, v72, v80, s88
	v_add3_u32 v73, v73, v81, s88
	v_add3_u32 v74, v74, v82, s88
	v_add3_u32 v75, v75, v83, s88
	v_add3_u32 v76, v76, v84, s88
	v_add3_u32 v77, v77, v85, s88
	v_add3_u32 v78, v78, v86, s88
	v_add3_u32 v79, v79, v87, s88
	global_store_short_d16_hi v[56:57], v72, off
	global_store_short_d16_hi v[58:59], v73, off
	global_store_short_d16_hi v[60:61], v74, off
	global_store_short_d16_hi v[62:63], v75, off
	global_store_short_d16_hi v[64:65], v76, off
	global_store_short_d16_hi v[66:67], v77, off
	global_store_short_d16_hi v[68:69], v78, off
	global_store_short_d16_hi v[70:71], v79, off
	s_lshl_b32 s98, s5, 1
	s_add_i32 s98, s98, s10
	s_cmp_lt_i32 s98, 0x580
	s_cbranch_scc0 .Lcv334_s1
	s_mul_hi_i32 s8, s98, 0x2e8ba2e9
	s_lshr_b32 s9, s8, 31
	s_ashr_i32 s8, s8, 8
	s_add_i32 s8, s8, s9
	s_mulk_i32 s8, 0x580
	s_sub_i32 s8, s98, s8
	s_sext_i32_i16 s9, s8
	s_bfe_u32 s9, s9, 0x4001b
	s_add_i32 s9, s8, s9
	s_sext_i32_i16 s11, s9
	s_lshl_b32 s11, s11, 2
	s_and_b32 s9, s9, 0xfff0
	s_andn2_b32 s11, s11, 63
	s_sub_i32 s8, s8, s9
	v_or_b32_e32 v56, s11, v4
	s_sext_i32_i16 s8, s8
	v_ashrrev_i32_e32 v57, 1, v56
	s_lshl_b32 s8, s8, 6
	v_and_or_b32 v58, v57, -16, v6
	v_add_u32_e32 v56, s8, v5
	v_ashrrev_i32_e32 v59, 31, v58
	v_ashrrev_i32_e32 v57, 31, v56
	v_lshl_add_u64 v[58:59], v[58:59], 2, v[0:1]
	v_add_u32_e32 v62, s8, v8
	v_add_u32_e32 v63, s8, v9
	v_add_u32_e32 v64, s8, v10
	v_add_u32_e32 v66, s8, v11
	v_add_u32_e32 v68, s8, v12
	v_add_u32_e32 v70, s8, v13
	v_add_u32_e32 v72, s8, v14
	v_lshl_add_u64 v[60:61], v[56:57], 2, s[6:7]
	v_mad_i64_i32 v[56:57], s[16:17], v56, s33, v[58:59]
	global_load_dword v74, v[60:61], off
	global_load_dword v75, v[60:61], off offset:32
	global_load_dword v76, v[60:61], off offset:64
	global_load_dword v77, v[60:61], off offset:96
	global_load_dword v78, v[60:61], off offset:128
	global_load_dword v79, v[60:61], off offset:160
	global_load_dword v80, v[60:61], off offset:192
	global_load_dword v81, v[60:61], off offset:224
	v_mad_i64_i32 v[60:61], s[16:17], v62, s33, v[58:59]
	v_mad_i64_i32 v[62:63], s[16:17], v63, s33, v[58:59]
	v_mad_i64_i32 v[64:65], s[16:17], v64, s33, v[58:59]
	v_mad_i64_i32 v[66:67], s[16:17], v66, s33, v[58:59]
	v_mad_i64_i32 v[68:69], s[16:17], v68, s33, v[58:59]
	v_mad_i64_i32 v[70:71], s[16:17], v70, s33, v[58:59]
	v_mad_i64_i32 v[58:59], s[16:17], v72, s33, v[58:59]
	global_load_dword v82, v[56:57], off
	global_load_dword v83, v[60:61], off
	global_load_dword v84, v[62:63], off
	global_load_dword v85, v[64:65], off
	global_load_dword v86, v[66:67], off
	global_load_dword v87, v[68:69], off
	global_load_dword v88, v[70:71], off
	global_load_dword v89, v[58:59], off
	v_add_u32_e32 v56, s11, v5
	v_add_u32_e32 v58, s11, v8
	v_add_u32_e32 v60, s11, v9
	v_add_u32_e32 v62, s11, v10
	v_add_u32_e32 v64, s11, v11
	v_add_u32_e32 v66, s11, v12
	v_add_u32_e32 v68, s11, v13
	v_add_u32_e32 v70, s11, v14
	s_ashr_i32 s9, s8, 31
	v_ashrrev_i32_e32 v57, 31, v56
	v_ashrrev_i32_e32 v59, 31, v58
	v_ashrrev_i32_e32 v61, 31, v60
	v_ashrrev_i32_e32 v63, 31, v62
	v_ashrrev_i32_e32 v65, 31, v64
	v_ashrrev_i32_e32 v67, 31, v66
	v_ashrrev_i32_e32 v69, 31, v68
	v_ashrrev_i32_e32 v71, 31, v70
	v_lshl_add_u64 v[72:73], s[8:9], 1, v[2:3]
	v_lshlrev_b64 v[56:57], 11, v[56:57]
	v_lshlrev_b64 v[58:59], 11, v[58:59]
	v_lshlrev_b64 v[60:61], 11, v[60:61]
	v_lshlrev_b64 v[62:63], 11, v[62:63]
	v_lshlrev_b64 v[64:65], 11, v[64:65]
	v_lshlrev_b64 v[66:67], 11, v[66:67]
	v_lshlrev_b64 v[68:69], 11, v[68:69]
	v_lshlrev_b64 v[70:71], 11, v[70:71]
	v_lshl_add_u64 v[56:57], v[72:73], 0, v[56:57]
	v_lshl_add_u64 v[58:59], v[72:73], 0, v[58:59]
	v_lshl_add_u64 v[60:61], v[72:73], 0, v[60:61]
	v_lshl_add_u64 v[62:63], v[72:73], 0, v[62:63]
	v_lshl_add_u64 v[64:65], v[72:73], 0, v[64:65]
	v_lshl_add_u64 v[66:67], v[72:73], 0, v[66:67]
	v_lshl_add_u64 v[68:69], v[72:73], 0, v[68:69]
	v_lshl_add_u64 v[70:71], v[72:73], 0, v[70:71]
	s_branch .Lcv334_n1

; __device__ __forceinline__ bf16_t f2bf(float f) { unsigned u = __float_as_uint(f); u += 0x7FFFu + ((u >> 16) & 1u); return (bf16_t)(u >> 16); }
;     ...
;     for (int t_ = first; t_ < ntile * ((REP & 1) + 1); t_ += gridDim.x) { const int t = t_ % ntile;
;         const int r0 = (t / nkt) * 64, k0 = (t % nkt) * 64;
;         __syncthreads();
; #pragma unroll
;         for (int i = 0; i < 8; ++i) { const int kk = i * 8 + w; tile[kk * 65 + lane] = src(k0 + kk, r0 + lane); }
;         __syncthreads();
; #pragma unroll
;         for (int i = 0; i < 8; ++i) { const int j = i * 8 + w; Bt[(size_t)(r0 + j) * ld + k0 + lane] = f2bf(tile[lane * 65 + j]); }
; __device__ void convert_phase(unsigned char* smem, const Params& p, int l) {
;     ...
;     { const float* wd = ((const float*)ldp(35)) + uo; conv_tiles(tile, wt + W_DN2, 1024, 2816, 97, [=](int k, int r) { return wd[(size_t)k * DM + r]; }); }
.Lcv337_top:
	s_waitcnt vmcnt(23)
	ds_write_b32 v12, v13
	s_waitcnt vmcnt(22)
	ds_write_b32 v12, v30 offset:2080
	s_waitcnt vmcnt(21)
	ds_write_b32 v12, v31 offset:4160
	s_waitcnt vmcnt(20)
	ds_write_b32 v12, v32 offset:6240
	s_waitcnt vmcnt(19)
	ds_write_b32 v12, v33 offset:8320
	s_waitcnt vmcnt(18)
	ds_write_b32 v12, v34 offset:10400
	s_waitcnt vmcnt(17)
	ds_write_b32 v12, v35 offset:12480
	s_waitcnt vmcnt(16)
	ds_write_b32 v12, v36 offset:14560
	s_waitcnt lgkmcnt(0)
	s_barrier
	ds_read2_b32 v[30:31], v4 offset1:8
	ds_read2_b32 v[32:33], v4 offset0:16 offset1:24
	ds_read2_b32 v[34:35], v4 offset0:32 offset1:40
	ds_read2_b32 v[36:37], v4 offset0:48 offset1:56
	s_waitcnt lgkmcnt(3)
	v_bfe_u32 v13, v30, 16, 1
	v_bfe_u32 v38, v31, 16, 1
	s_waitcnt lgkmcnt(2)
	v_bfe_u32 v39, v32, 16, 1
	v_bfe_u32 v40, v33, 16, 1
	s_waitcnt lgkmcnt(1)
	v_bfe_u32 v41, v34, 16, 1
	v_bfe_u32 v42, v35, 16, 1
	s_waitcnt lgkmcnt(0)
	v_bfe_u32 v43, v36, 16, 1
	v_bfe_u32 v44, v37, 16, 1
	v_add3_u32 v13, v30, v13, s88
	v_add3_u32 v30, v31, v38, s88
	v_add3_u32 v31, v32, v39, s88
	v_add3_u32 v32, v33, v40, s88
	v_add3_u32 v33, v34, v41, s88
	v_add3_u32 v34, v35, v42, s88
	v_add3_u32 v35, v36, v43, s88
	v_add3_u32 v36, v37, v44, s88
	global_store_short_d16_hi v[16:17], v13, off
	global_store_short_d16_hi v[18:19], v30, off
	global_store_short_d16_hi v[20:21], v31, off
	global_store_short_d16_hi v[22:23], v32, off
	global_store_short_d16_hi v[24:25], v33, off
	global_store_short_d16_hi v[26:27], v34, off
	global_store_short_d16_hi v[28:29], v35, off
	global_store_short_d16_hi v[14:15], v36, off
	s_lshl_b32 s98, s5, 1
	s_add_i32 s98, s98, s10
	s_cmp_lt_i32 s98, 0x2c0
	s_cbranch_scc0 .Lcv337_s0
	s_mul_hi_i32 s8, s98, 0x2e8ba2e9
	s_lshr_b32 s9, s8, 31
	s_ashr_i32 s8, s8, 7
	s_add_i32 s8, s8, s9
	s_mulk_i32 s8, 0x2c0
	s_sub_i32 s8, s98, s8
	s_sext_i32_i16 s9, s8
	s_mulk_i32 s9, 0xba3
	s_lshr_b32 s11, s9, 31
	s_ashr_i32 s9, s9, 17
	s_add_i32 s9, s9, s11
	s_sext_i32_i16 s11, s9
	s_mul_i32 s9, s9, 44
	s_sub_i32 s8, s8, s9
	s_sext_i32_i16 s8, s8
	s_lshl_b32 s11, s11, 6
	s_lshl_b32 s8, s8, 6
	v_or_b32_e32 v14, s11, v2
	v_add_u32_e32 v16, s8, v3
	v_ashrrev_i32_e32 v15, 31, v14
	v_add_u32_e32 v18, s8, v5
	v_add_u32_e32 v20, s8, v6
	v_add_u32_e32 v22, s8, v7
	v_add_u32_e32 v24, s8, v8
	v_add_u32_e32 v26, s8, v9
	v_add_u32_e32 v28, s8, v10
	v_add_u32_e32 v30, s8, v11
	v_ashrrev_i32_e32 v17, 31, v16
	v_lshl_add_u64 v[14:15], v[14:15], 2, s[6:7]
	v_ashrrev_i32_e32 v19, 31, v18
	v_ashrrev_i32_e32 v21, 31, v20
	v_ashrrev_i32_e32 v23, 31, v22
	v_ashrrev_i32_e32 v25, 31, v24
	v_ashrrev_i32_e32 v27, 31, v26
	v_ashrrev_i32_e32 v29, 31, v28
	v_ashrrev_i32_e32 v31, 31, v30
	v_lshlrev_b64 v[16:17], 12, v[16:17]
	v_lshlrev_b64 v[18:19], 12, v[18:19]
	v_lshlrev_b64 v[20:21], 12, v[20:21]
	v_lshlrev_b64 v[22:23], 12, v[22:23]
	v_lshlrev_b64 v[24:25], 12, v[24:25]
	v_lshlrev_b64 v[26:27], 12, v[26:27]
	v_lshlrev_b64 v[28:29], 12, v[28:29]
	v_lshlrev_b64 v[30:31], 12, v[30:31]
	v_lshl_add_u64 v[16:17], v[14:15], 0, v[16:17]
	v_lshl_add_u64 v[18:19], v[14:15], 0, v[18:19]
	v_lshl_add_u64 v[20:21], v[14:15], 0, v[20:21]
	v_lshl_add_u64 v[22:23], v[14:15], 0, v[22:23]
	v_lshl_add_u64 v[24:25], v[14:15], 0, v[24:25]
	v_lshl_add_u64 v[26:27], v[14:15], 0, v[26:27]
	v_lshl_add_u64 v[28:29], v[14:15], 0, v[28:29]
	v_lshl_add_u64 v[14:15], v[14:15], 0, v[30:31]
	global_load_dword v13, v[16:17], off
	global_load_dword v30, v[18:19], off
	global_load_dword v31, v[20:21], off
	global_load_dword v32, v[22:23], off
	global_load_dword v33, v[24:25], off
	global_load_dword v34, v[26:27], off
	global_load_dword v35, v[28:29], off
	global_load_dword v36, v[14:15], off
	s_ashr_i32 s9, s8, 31
	v_add_u32_e32 v16, s11, v3
	v_add_u32_e32 v18, s11, v5
	v_add_u32_e32 v20, s11, v6
	v_add_u32_e32 v22, s11, v7
	v_add_u32_e32 v24, s11, v8
	v_add_u32_e32 v26, s11, v9
	v_add_u32_e32 v28, s11, v10
	v_add_u32_e32 v37, s11, v11
	v_lshl_add_u64 v[14:15], s[8:9], 1, v[0:1]
	v_mad_i64_i32 v[16:17], s[8:9], v16, s54, v[14:15]
	v_mad_i64_i32 v[18:19], s[8:9], v18, s54, v[14:15]
	v_mad_i64_i32 v[20:21], s[8:9], v20, s54, v[14:15]
	v_mad_i64_i32 v[22:23], s[8:9], v22, s54, v[14:15]
	v_mad_i64_i32 v[24:25], s[8:9], v24, s54, v[14:15]
	v_mad_i64_i32 v[26:27], s[8:9], v26, s54, v[14:15]
	v_mad_i64_i32 v[28:29], s[8:9], v28, s54, v[14:15]
	v_mad_i64_i32 v[14:15], s[8:9], v37, s54, v[14:15]
	s_branch .Lcv337_n0

; __device__ __forceinline__ bf16_t f2bf(float f) { unsigned u = __float_as_uint(f); u += 0x7FFFu + ((u >> 16) & 1u); return (bf16_t)(u >> 16); }
;     ...
;     for (int t_ = first; t_ < ntile * ((REP & 1) + 1); t_ += gridDim.x) { const int t = t_ % ntile;
;         const int r0 = (t / nkt) * 64, k0 = (t % nkt) * 64;
;         __syncthreads();
; #pragma unroll
;         for (int i = 0; i < 8; ++i) { const int kk = i * 8 + w; tile[kk * 65 + lane] = src(k0 + kk, r0 + lane); }
;         __syncthreads();
; #pragma unroll
;         for (int i = 0; i < 8; ++i) { const int j = i * 8 + w; Bt[(size_t)(r0 + j) * ld + k0 + lane] = f2bf(tile[lane * 65 + j]); }
; __device__ void convert_phase(unsigned char* smem, const Params& p, int l) {
;     ...
;     { const float* wd = ((const float*)ldp(35)) + uo; conv_tiles(tile, wt + W_DN2, 1024, 2816, 97, [=](int k, int r) { return wd[(size_t)k * DM + r]; }); }
.Lcv337_n0:
	s_add_i32 s10, s10, s5
	s_cmp_lt_i32 s10, 0x2c0
	s_cbranch_scc0 .LBB0_338
	s_waitcnt vmcnt(23)
	ds_write_b32 v12, v53 offset:17408
	s_waitcnt vmcnt(22)
	ds_write_b32 v12, v70 offset:19488
	s_waitcnt vmcnt(21)
	ds_write_b32 v12, v71 offset:21568
	s_waitcnt vmcnt(20)
	ds_write_b32 v12, v72 offset:23648
	s_waitcnt vmcnt(19)
	ds_write_b32 v12, v73 offset:25728
	s_waitcnt vmcnt(18)
	ds_write_b32 v12, v74 offset:27808
	s_waitcnt vmcnt(17)
	ds_write_b32 v12, v75 offset:29888
	s_waitcnt vmcnt(16)
	ds_write_b32 v12, v76 offset:31968
	s_waitcnt lgkmcnt(0)
	s_barrier
	ds_read2_b32 v[70:71], v95 offset1:8
	ds_read2_b32 v[72:73], v95 offset0:16 offset1:24
	ds_read2_b32 v[74:75], v95 offset0:32 offset1:40
	ds_read2_b32 v[76:77], v95 offset0:48 offset1:56
	s_waitcnt lgkmcnt(3)
	v_bfe_u32 v53, v70, 16, 1
	v_bfe_u32 v78, v71, 16, 1
	s_waitcnt lgkmcnt(2)
	v_bfe_u32 v79, v72, 16, 1
	v_bfe_u32 v80, v73, 16, 1
	s_waitcnt lgkmcnt(1)
	v_bfe_u32 v81, v74, 16, 1
	v_bfe_u32 v82, v75, 16, 1
	s_waitcnt lgkmcnt(0)
	v_bfe_u32 v83, v76, 16, 1
	v_bfe_u32 v84, v77, 16, 1
	v_add3_u32 v53, v70, v53, s88
	v_add3_u32 v70, v71, v78, s88
	v_add3_u32 v71, v72, v79, s88
	v_add3_u32 v72, v73, v80, s88
	v_add3_u32 v73, v74, v81, s88
	v_add3_u32 v74, v75, v82, s88
	v_add3_u32 v75, v76, v83, s88
	v_add3_u32 v76, v77, v84, s88
	global_store_short_d16_hi v[56:57], v53, off
	global_store_short_d16_hi v[58:59], v70, off
	global_store_short_d16_hi v[60:61], v71, off
	global_store_short_d16_hi v[62:63], v72, off
	global_store_short_d16_hi v[64:65], v73, off
	global_store_short_d16_hi v[66:67], v74, off
	global_store_short_d16_hi v[68:69], v75, off
	global_store_short_d16_hi v[54:55], v76, off
	s_lshl_b32 s98, s5, 1
	s_add_i32 s98, s98, s10
	s_cmp_lt_i32 s98, 0x2c0
	s_cbranch_scc0 .Lcv337_s1
	s_mul_hi_i32 s8, s98, 0x2e8ba2e9
	s_lshr_b32 s9, s8, 31
	s_ashr_i32 s8, s8, 7
	s_add_i32 s8, s8, s9
	s_mulk_i32 s8, 0x2c0
	s_sub_i32 s8, s98, s8
	s_sext_i32_i16 s9, s8
	s_mulk_i32 s9, 0xba3
	s_lshr_b32 s11, s9, 31
	s_ashr_i32 s9, s9, 17
	s_add_i32 s9, s9, s11
	s_sext_i32_i16 s11, s9
	s_mul_i32 s9, s9, 44
	s_sub_i32 s8, s8, s9
	s_sext_i32_i16 s8, s8
	s_lshl_b32 s11, s11, 6
	s_lshl_b32 s8, s8, 6
	v_or_b32_e32 v54, s11, v2
	v_add_u32_e32 v56, s8, v3
	v_ashrrev_i32_e32 v55, 31, v54
	v_add_u32_e32 v58, s8, v5
	v_add_u32_e32 v60, s8, v6
	v_add_u32_e32 v62, s8, v7
	v_add_u32_e32 v64, s8, v8
	v_add_u32_e32 v66, s8, v9
	v_add_u32_e32 v68, s8, v10
	v_add_u32_e32 v70, s8, v11
	v_ashrrev_i32_e32 v57, 31, v56
	v_lshl_add_u64 v[54:55], v[54:55], 2, s[6:7]
	v_ashrrev_i32_e32 v59, 31, v58
	v_ashrrev_i32_e32 v61, 31, v60
	v_ashrrev_i32_e32 v63, 31, v62
	v_ashrrev_i32_e32 v65, 31, v64
	v_ashrrev_i32_e32 v67, 31, v66
	v_ashrrev_i32_e32 v69, 31, v68
	v_ashrrev_i32_e32 v71, 31, v70
	v_lshlrev_b64 v[56:57], 12, v[56:57]
	v_lshlrev_b64 v[58:59], 12, v[58:59]
	v_lshlrev_b64 v[60:61], 12, v[60:61]
	v_lshlrev_b64 v[62:63], 12, v[62:63]
	v_lshlrev_b64 v[64:65], 12, v[64:65]
	v_lshlrev_b64 v[66:67], 12, v[66:67]
	v_lshlrev_b64 v[68:69], 12, v[68:69]
	v_lshlrev_b64 v[70:71], 12, v[70:71]
	v_lshl_add_u64 v[56:57], v[54:55], 0, v[56:57]
	v_lshl_add_u64 v[58:59], v[54:55], 0, v[58:59]
	v_lshl_add_u64 v[60:61], v[54:55], 0, v[60:61]
	v_lshl_add_u64 v[62:63], v[54:55], 0, v[62:63]
	v_lshl_add_u64 v[64:65], v[54:55], 0, v[64:65]
	v_lshl_add_u64 v[66:67], v[54:55], 0, v[66:67]
	v_lshl_add_u64 v[68:69], v[54:55], 0, v[68:69]
	v_lshl_add_u64 v[54:55], v[54:55], 0, v[70:71]
	global_load_dword v53, v[56:57], off
	global_load_dword v70, v[58:59], off
	global_load_dword v71, v[60:61], off
	global_load_dword v72, v[62:63], off
	global_load_dword v73, v[64:65], off
	global_load_dword v74, v[66:67], off
	global_load_dword v75, v[68:69], off
	global_load_dword v76, v[54:55], off
	s_ashr_i32 s9, s8, 31
	v_add_u32_e32 v56, s11, v3
	v_add_u32_e32 v58, s11, v5
	v_add_u32_e32 v60, s11, v6
	v_add_u32_e32 v62, s11, v7
	v_add_u32_e32 v64, s11, v8
	v_add_u32_e32 v66, s11, v9
	v_add_u32_e32 v68, s11, v10
	v_add_u32_e32 v77, s11, v11
	v_lshl_add_u64 v[54:55], s[8:9], 1, v[0:1]
	v_mad_i64_i32 v[56:57], s[8:9], v56, s54, v[54:55]
	v_mad_i64_i32 v[58:59], s[8:9], v58, s54, v[54:55]
	v_mad_i64_i32 v[60:61], s[8:9], v60, s54, v[54:55]
	v_mad_i64_i32 v[62:63], s[8:9], v62, s54, v[54:55]
	v_mad_i64_i32 v[64:65], s[8:9], v64, s54, v[54:55]
	v_mad_i64_i32 v[66:67], s[8:9], v66, s54, v[54:55]
	v_mad_i64_i32 v[68:69], s[8:9], v68, s54, v[54:55]
	v_mad_i64_i32 v[54:55], s[8:9], v77, s54, v[54:55]
	s_branch .Lcv337_n1
